# prep phase stores and attention output stores also marked sc1 (written through the XCD L2 while streaming)
# baseline (speedup 1.0000x reference)
; __device__ __forceinline__ void phase_prep(KP kp, unsigned char* shm) {
;     ...
; #pragma unroll
;     for (int q = 0; q < 4; ++q) {
;       const TTile t = prep_tile(kp, ws, j0 + q);
; #pragma unroll
;       for (int e = 0; e < 4; ++e) {
;         const int idx = tid + e * 512, n = idx >> 5, kk = (idx & 31) * 2;
;         *(unsigned*)(t.dst + (size_t)(t.n0 + n) * t.K + t.k0 + kk) = cvt_pk_bf16(tl[q * 4160 + n * 65 + kk], tl[q * 4160 + n * 65 + kk + 1]);
;       }
;     }
;     __syncthreads();
.LBB0_7:
	s_ashr_i32 s5, s4, 31
	v_add3_u32 v4, v18, v20, s71
	s_lshl_b64 s[4:5], s[4:5], 1
	ds_read2_b32 v[4:5], v4 offset1:1
	s_add_u32 s2, s2, s4
	v_add_u32_e32 v46, s8, v19
	s_addc_u32 s3, s3, s5
	s_waitcnt lgkmcnt(0)
	v_cvt_pk_bf16_f32 v45, v4, v5
	v_ashrrev_i32_e32 v4, 31, v46
	v_lshl_add_u64 v[6:7], s[2:3], 0, v[2:3]
	v_mul_lo_u32 v48, s0, v4
	v_mul_lo_u32 v49, s1, v46
	v_mad_u64_u32 v[46:47], s[2:3], s0, v46, 0
	v_add3_u32 v47, v47, v48, v49
	v_add3_u32 v4, v18, v39, s71
	v_lshl_add_u64 v[46:47], v[46:47], 1, v[6:7]
	ds_read2_b32 v[4:5], v4 offset1:1
	global_store_dword v[46:47], v45, off sc1
	v_add_u32_e32 v46, s8, v38
	s_waitcnt lgkmcnt(0)
	v_cvt_pk_bf16_f32 v45, v4, v5
	v_ashrrev_i32_e32 v4, 31, v46
	v_mul_lo_u32 v48, s0, v4
	v_mul_lo_u32 v49, s1, v46
	v_mad_u64_u32 v[46:47], s[2:3], s0, v46, 0
	v_add3_u32 v47, v47, v48, v49
	v_add3_u32 v4, v18, v41, s71
	v_lshl_add_u64 v[46:47], v[46:47], 1, v[6:7]
	ds_read2_b32 v[4:5], v4 offset1:1
	global_store_dword v[46:47], v45, off sc1
	v_add_u32_e32 v46, s8, v40
	s_waitcnt lgkmcnt(0)
	v_cvt_pk_bf16_f32 v45, v4, v5
	v_ashrrev_i32_e32 v4, 31, v46
	v_mul_lo_u32 v48, s0, v4
	v_mul_lo_u32 v49, s1, v46
	v_mad_u64_u32 v[46:47], s[2:3], s0, v46, 0
	v_add3_u32 v4, v18, v43, s71
	v_add3_u32 v47, v47, v48, v49
	ds_read2_b32 v[4:5], v4 offset1:1
	v_lshl_add_u64 v[46:47], v[46:47], 1, v[6:7]
	global_store_dword v[46:47], v45, off sc1
	s_waitcnt lgkmcnt(0)
	v_cvt_pk_bf16_f32 v45, v4, v5
	v_add_u32_e32 v4, s8, v42
	v_ashrrev_i32_e32 v5, 31, v4
	v_mul_lo_u32 v46, s0, v5
	v_mul_lo_u32 v47, s1, v4
	v_mad_u64_u32 v[4:5], s[0:1], s0, v4, 0
	v_add3_u32 v5, v5, v46, v47
	s_add_i32 s46, s46, s33
	s_add_i32 s54, s54, s55
	s_add_i32 s56, s56, s57
	s_add_i32 s58, s58, s59
	s_add_i32 s60, s60, s61
	s_add_i32 s62, s62, s63
	v_lshl_add_u64 v[4:5], v[4:5], 1, v[6:7]
	s_cmpk_gt_i32 s46, 0x1c7f
	global_store_dword v[4:5], v45, off sc1
	s_barrier
	s_cbranch_scc1 .LBB0_2220

; __device__ __forceinline__ TTile prep_tile(KP kp, unsigned char* ws, int j) {
;     ...
;   if (jj < 2048) {
;     const int l = jj / 1024, q = jj % 1024;
;     t.src = kp->w_ff1 + (size_t)l * 1024 * 4096; t.ldsrc = 4096; t.dst = (bf16_t*)(ws + W_FF1) + (size_t)l * 4096 * 1024; t.K = 1024; t.n0 = (q / 16) * 64; t.k0 = (q % 16) * 64;
;     return t;
;   }
;   jj -= 2048;
;   {
;     const int l = jj / 1024, q = jj % 1024;
;     t.src = kp->w_ff2 + (size_t)l * 4096 * 1024; t.ldsrc = 1024; t.dst = (bf16_t*)(ws + W_FF2) + (size_t)l * 1024 * LDH; t.K = LDH; t.n0 = (q / 64) * 64; t.k0 = (q % 64) * 64;
;   }
; __device__ __forceinline__ void phase_prep(KP kp, unsigned char* shm) {
;     ...
;     for (int q = 0; q < 4; ++q) {
;       const TTile t = prep_tile(kp, ws, j0 + q);
; #pragma unroll
;       for (int e = 0; e < 4; ++e) {
;         const int idx = tid + e * 512, n = idx >> 5, kk = (idx & 31) * 2;
;         *(unsigned*)(t.dst + (size_t)(t.n0 + n) * t.K + t.k0 + kk) = cvt_pk_bf16(tl[q * 4160 + n * 65 + kk], tl[q * 4160 + n * 65 + kk + 1]);
;       }
.LBB0_2102:
	s_ashr_i32 s5, s4, 31
	v_add_u32_e32 v4, v18, v20
	s_lshl_b64 s[4:5], s[4:5], 1
	ds_read2_b32 v[4:5], v4 offset1:1
	s_add_u32 s2, s2, s4
	v_add_u32_e32 v46, s8, v19
	s_addc_u32 s3, s3, s5
	s_waitcnt lgkmcnt(0)
	v_cvt_pk_bf16_f32 v45, v4, v5
	v_ashrrev_i32_e32 v4, 31, v46
	v_lshl_add_u64 v[6:7], s[2:3], 0, v[2:3]
	v_mul_lo_u32 v48, s0, v4
	v_mul_lo_u32 v49, s1, v46
	v_mad_u64_u32 v[46:47], s[2:3], s0, v46, 0
	v_add3_u32 v47, v47, v48, v49
	v_add_u32_e32 v4, v18, v39
	v_lshl_add_u64 v[46:47], v[46:47], 1, v[6:7]
	ds_read2_b32 v[4:5], v4 offset1:1
	global_store_dword v[46:47], v45, off sc1
	v_add_u32_e32 v46, s8, v38
	s_waitcnt lgkmcnt(0)
	v_cvt_pk_bf16_f32 v45, v4, v5
	v_ashrrev_i32_e32 v4, 31, v46
	v_mul_lo_u32 v48, s0, v4
	v_mul_lo_u32 v49, s1, v46
	v_mad_u64_u32 v[46:47], s[2:3], s0, v46, 0
	v_add3_u32 v47, v47, v48, v49
	v_add_u32_e32 v4, v18, v41
	v_lshl_add_u64 v[46:47], v[46:47], 1, v[6:7]
	ds_read2_b32 v[4:5], v4 offset1:1
	global_store_dword v[46:47], v45, off sc1
	v_add_u32_e32 v46, s8, v40
	s_waitcnt lgkmcnt(0)
	v_cvt_pk_bf16_f32 v45, v4, v5
	v_ashrrev_i32_e32 v4, 31, v46
	v_mul_lo_u32 v48, s0, v4
	v_mul_lo_u32 v49, s1, v46
	v_mad_u64_u32 v[46:47], s[2:3], s0, v46, 0
	v_add_u32_e32 v4, v18, v43
	v_add3_u32 v47, v47, v48, v49
	ds_read2_b32 v[4:5], v4 offset1:1
	v_lshl_add_u64 v[46:47], v[46:47], 1, v[6:7]
	global_store_dword v[46:47], v45, off sc1
	s_waitcnt lgkmcnt(0)
	v_cvt_pk_bf16_f32 v45, v4, v5
	v_add_u32_e32 v4, s8, v42
	v_ashrrev_i32_e32 v5, 31, v4
	v_mul_lo_u32 v46, s0, v5
	v_mul_lo_u32 v47, s1, v4
	v_mad_u64_u32 v[4:5], s[0:1], s0, v4, 0
	v_add3_u32 v5, v5, v46, v47
	v_lshl_add_u64 v[4:5], v[4:5], 1, v[6:7]
	s_andn2_b64 vcc, exec, s[28:29]
	s_mov_b64 s[6:7], -1
	global_store_dword v[4:5], v45, off sc1
	s_cbranch_vccnz .LBB0_2116
	s_cmpk_lt_u32 s46, 0xa80
	s_cbranch_scc1 .LBB0_2113
	s_cmpk_lt_u32 s46, 0xc80
	s_cbranch_scc1 .LBB0_2110
	s_cmpk_lt_u32 s46, 0x1480
	s_mov_b64 s[0:1], -1
	s_cbranch_scc1 .LBB0_2107
	s_add_i32 s0, s46, 0xffffeb81
	s_lshr_b32 s1, s0, 10
	s_mul_hi_u32 s3, s1, 0x820000
	s_mul_i32 s1, s1, 0x820000
	s_add_u32 s2, s47, s1
	s_addc_u32 s3, s49, s3
	s_and_b32 s8, s0, 0x3c0
	s_add_i32 s0, s58, 64
	s_and_b32 s4, s0, 0xf40
	s_mov_b64 s[0:1], 0

; __device__ __forceinline__ TTile prep_tile(KP kp, unsigned char* ws, int j) {
;     ...
;   if (jj < 2048) {
;     const int l = jj / 1024, q = jj % 1024;
;     t.src = kp->w_ff1 + (size_t)l * 1024 * 4096; t.ldsrc = 4096; t.dst = (bf16_t*)(ws + W_FF1) + (size_t)l * 4096 * 1024; t.K = 1024; t.n0 = (q / 16) * 64; t.k0 = (q % 16) * 64;
;     return t;
;   }
;   jj -= 2048;
;   {
;     const int l = jj / 1024, q = jj % 1024;
;     t.src = kp->w_ff2 + (size_t)l * 4096 * 1024; t.ldsrc = 1024; t.dst = (bf16_t*)(ws + W_FF2) + (size_t)l * 1024 * LDH; t.K = LDH; t.n0 = (q / 64) * 64; t.k0 = (q % 64) * 64;
;   }
; __device__ __forceinline__ void phase_prep(KP kp, unsigned char* shm) {
;     ...
;     for (int q = 0; q < 4; ++q) {
;       const TTile t = prep_tile(kp, ws, j0 + q);
; #pragma unroll
;       for (int e = 0; e < 4; ++e) {
;         const int idx = tid + e * 512, n = idx >> 5, kk = (idx & 31) * 2;
;         *(unsigned*)(t.dst + (size_t)(t.n0 + n) * t.K + t.k0 + kk) = cvt_pk_bf16(tl[q * 4160 + n * 65 + kk], tl[q * 4160 + n * 65 + kk + 1]);
;       }
.LBB0_2118:
	s_ashr_i32 s5, s4, 31
	v_add3_u32 v4, v18, v20, s69
	s_lshl_b64 s[4:5], s[4:5], 1
	ds_read2_b32 v[4:5], v4 offset1:1
	s_add_u32 s2, s2, s4
	v_add_u32_e32 v46, s8, v19
	s_addc_u32 s3, s3, s5
	s_waitcnt lgkmcnt(0)
	v_cvt_pk_bf16_f32 v45, v4, v5
	v_ashrrev_i32_e32 v4, 31, v46
	v_lshl_add_u64 v[6:7], s[2:3], 0, v[2:3]
	v_mul_lo_u32 v48, s0, v4
	v_mul_lo_u32 v49, s1, v46
	v_mad_u64_u32 v[46:47], s[2:3], s0, v46, 0
	v_add3_u32 v47, v47, v48, v49
	v_add3_u32 v4, v18, v39, s69
	v_lshl_add_u64 v[46:47], v[46:47], 1, v[6:7]
	ds_read2_b32 v[4:5], v4 offset1:1
	global_store_dword v[46:47], v45, off sc1
	v_add_u32_e32 v46, s8, v38
	s_waitcnt lgkmcnt(0)
	v_cvt_pk_bf16_f32 v45, v4, v5
	v_ashrrev_i32_e32 v4, 31, v46
	v_mul_lo_u32 v48, s0, v4
	v_mul_lo_u32 v49, s1, v46
	v_mad_u64_u32 v[46:47], s[2:3], s0, v46, 0
	v_add3_u32 v47, v47, v48, v49
	v_add3_u32 v4, v18, v41, s69
	v_lshl_add_u64 v[46:47], v[46:47], 1, v[6:7]
	ds_read2_b32 v[4:5], v4 offset1:1
	global_store_dword v[46:47], v45, off sc1
	v_add_u32_e32 v46, s8, v40
	s_waitcnt lgkmcnt(0)
	v_cvt_pk_bf16_f32 v45, v4, v5
	v_ashrrev_i32_e32 v4, 31, v46
	v_mul_lo_u32 v48, s0, v4
	v_mul_lo_u32 v49, s1, v46
	v_mad_u64_u32 v[46:47], s[2:3], s0, v46, 0
	v_add3_u32 v4, v18, v43, s69
	v_add3_u32 v47, v47, v48, v49
	ds_read2_b32 v[4:5], v4 offset1:1
	v_lshl_add_u64 v[46:47], v[46:47], 1, v[6:7]
	global_store_dword v[46:47], v45, off sc1
	s_waitcnt lgkmcnt(0)
	v_cvt_pk_bf16_f32 v45, v4, v5
	v_add_u32_e32 v4, s8, v42
	v_ashrrev_i32_e32 v5, 31, v4
	v_mul_lo_u32 v46, s0, v5
	v_mul_lo_u32 v47, s1, v4
	v_mad_u64_u32 v[4:5], s[0:1], s0, v4, 0
	v_add3_u32 v5, v5, v46, v47
	v_lshl_add_u64 v[4:5], v[4:5], 1, v[6:7]
	s_andn2_b64 vcc, exec, s[30:31]
	s_mov_b64 s[6:7], -1
	global_store_dword v[4:5], v45, off sc1
	s_cbranch_vccnz .LBB0_2132
	s_cmpk_lt_u32 s46, 0xa80
	s_cbranch_scc1 .LBB0_2129
	s_cmpk_lt_u32 s46, 0xc80
	s_cbranch_scc1 .LBB0_2126
	s_cmpk_lt_u32 s46, 0x1480
	s_mov_b64 s[0:1], -1
	s_cbranch_scc1 .LBB0_2123
	s_add_i32 s0, s46, 0xffffeb82
	s_lshr_b32 s1, s0, 10
	s_mul_hi_u32 s3, s1, 0x820000
	s_mul_i32 s1, s1, 0x820000
	s_add_u32 s2, s47, s1
	s_addc_u32 s3, s49, s3
	s_and_b32 s8, s0, 0x3c0
	s_add_i32 s0, s58, 0x80
	s_and_b32 s4, s0, 0xf80
	s_mov_b64 s[0:1], 0

; __device__ __forceinline__ TTile prep_tile(KP kp, unsigned char* ws, int j) {
;     ...
;   if (jj < 2048) {
;     const int l = jj / 1024, q = jj % 1024;
;     t.src = kp->w_ff1 + (size_t)l * 1024 * 4096; t.ldsrc = 4096; t.dst = (bf16_t*)(ws + W_FF1) + (size_t)l * 4096 * 1024; t.K = 1024; t.n0 = (q / 16) * 64; t.k0 = (q % 16) * 64;
;     return t;
;   }
;   jj -= 2048;
;   {
;     const int l = jj / 1024, q = jj % 1024;
;     t.src = kp->w_ff2 + (size_t)l * 4096 * 1024; t.ldsrc = 1024; t.dst = (bf16_t*)(ws + W_FF2) + (size_t)l * 1024 * LDH; t.K = LDH; t.n0 = (q / 64) * 64; t.k0 = (q % 64) * 64;
;   }
; __device__ __forceinline__ void phase_prep(KP kp, unsigned char* shm) {
;     ...
;     for (int q = 0; q < 4; ++q) {
;       const TTile t = prep_tile(kp, ws, j0 + q);
; #pragma unroll
;       for (int e = 0; e < 4; ++e) {
;         const int idx = tid + e * 512, n = idx >> 5, kk = (idx & 31) * 2;
;         *(unsigned*)(t.dst + (size_t)(t.n0 + n) * t.K + t.k0 + kk) = cvt_pk_bf16(tl[q * 4160 + n * 65 + kk], tl[q * 4160 + n * 65 + kk + 1]);
;       }
.LBB0_2134:
	s_ashr_i32 s5, s4, 31
	v_add3_u32 v4, v18, v20, s70
	s_lshl_b64 s[4:5], s[4:5], 1
	ds_read2_b32 v[4:5], v4 offset1:1
	s_add_u32 s2, s2, s4
	v_add_u32_e32 v46, s8, v19
	s_addc_u32 s3, s3, s5
	s_waitcnt lgkmcnt(0)
	v_cvt_pk_bf16_f32 v45, v4, v5
	v_ashrrev_i32_e32 v4, 31, v46
	v_lshl_add_u64 v[6:7], s[2:3], 0, v[2:3]
	v_mul_lo_u32 v48, s0, v4
	v_mul_lo_u32 v49, s1, v46
	v_mad_u64_u32 v[46:47], s[2:3], s0, v46, 0
	v_add3_u32 v47, v47, v48, v49
	v_add3_u32 v4, v18, v39, s70
	v_lshl_add_u64 v[46:47], v[46:47], 1, v[6:7]
	ds_read2_b32 v[4:5], v4 offset1:1
	global_store_dword v[46:47], v45, off sc1
	v_add_u32_e32 v46, s8, v38
	s_waitcnt lgkmcnt(0)
	v_cvt_pk_bf16_f32 v45, v4, v5
	v_ashrrev_i32_e32 v4, 31, v46
	v_mul_lo_u32 v48, s0, v4
	v_mul_lo_u32 v49, s1, v46
	v_mad_u64_u32 v[46:47], s[2:3], s0, v46, 0
	v_add3_u32 v47, v47, v48, v49
	v_add3_u32 v4, v18, v41, s70
	v_lshl_add_u64 v[46:47], v[46:47], 1, v[6:7]
	ds_read2_b32 v[4:5], v4 offset1:1
	global_store_dword v[46:47], v45, off sc1
	v_add_u32_e32 v46, s8, v40
	s_waitcnt lgkmcnt(0)
	v_cvt_pk_bf16_f32 v45, v4, v5
	v_ashrrev_i32_e32 v4, 31, v46
	v_mul_lo_u32 v48, s0, v4
	v_mul_lo_u32 v49, s1, v46
	v_mad_u64_u32 v[46:47], s[2:3], s0, v46, 0
	v_add3_u32 v4, v18, v43, s70
	v_add3_u32 v47, v47, v48, v49
	ds_read2_b32 v[4:5], v4 offset1:1
	v_lshl_add_u64 v[46:47], v[46:47], 1, v[6:7]
	global_store_dword v[46:47], v45, off sc1
	s_waitcnt lgkmcnt(0)
	v_cvt_pk_bf16_f32 v45, v4, v5
	v_add_u32_e32 v4, s8, v42
	v_ashrrev_i32_e32 v5, 31, v4
	v_mul_lo_u32 v46, s0, v5
	v_mul_lo_u32 v47, s1, v4
	v_mad_u64_u32 v[4:5], s[0:1], s0, v4, 0
	v_add3_u32 v5, v5, v46, v47
	v_lshl_add_u64 v[4:5], v[4:5], 1, v[6:7]
	s_andn2_b64 vcc, exec, s[34:35]
	s_mov_b64 s[6:7], -1
	global_store_dword v[4:5], v45, off sc1
	s_cbranch_vccnz .LBB0_2148
	s_cmpk_lt_u32 s46, 0xa80
	s_cbranch_scc1 .LBB0_2145
	s_cmpk_lt_u32 s46, 0xc80
	s_cbranch_scc1 .LBB0_2142
	s_cmpk_lt_u32 s46, 0x1480
	s_mov_b64 s[0:1], -1
	s_cbranch_scc1 .LBB0_2139
	s_add_i32 s0, s46, 0xffffeb83
	s_lshr_b32 s1, s0, 10
	s_mul_hi_u32 s3, s1, 0x820000
	s_mul_i32 s1, s1, 0x820000
	s_add_u32 s2, s47, s1
	s_addc_u32 s3, s49, s3
	s_and_b32 s8, s0, 0x3c0
	s_add_i32 s0, s58, 0xc0
	s_and_b32 s4, s0, 0xfc0
	s_mov_b64 s[0:1], 0

; __device__ __forceinline__ void cvt_rows(const float* __restrict__ src, bf16_t* __restrict__ dst, size_t n4, size_t gtid, size_t gn) {
;     ...
; #pragma unroll
;     for (int q = 0; q < 4; ++q) {
;       const size_t i = i0 + q * gn;
;       if (i < n4) { u32x2 w; w[0] = cvt_pk_bf16(v[q][0], v[q][1]); w[1] = cvt_pk_bf16(v[q][2], v[q][3]); *(u32x2*)(dst + i * 4) = w; }
;     }
.LBB0_2229:
	s_or_b64 exec, exec, s[42:43]
	s_waitcnt vmcnt(0)
	v_cvt_pk_bf16_f32 v10, v10, v11
	v_cvt_pk_bf16_f32 v11, v12, v13
	v_lshl_add_u64 v[12:13], s[40:41], 0, v[18:19]
	global_store_dwordx2 v[12:13], v[10:11], off sc1
	s_and_saveexec_b64 s[42:43], vcc
	s_cbranch_execz .LBB0_2232
	v_cvt_pk_bf16_f32 v6, v6, v7
	v_cvt_pk_bf16_f32 v7, v8, v9
	v_lshl_add_u64 v[8:9], s[40:41], 0, v[26:27]
	global_store_dwordx2 v[8:9], v[6:7], off sc1
	s_or_b64 exec, exec, s[42:43]
	s_and_saveexec_b64 s[42:43], s[0:1]
	s_cbranch_execnz .LBB0_2233

; __device__ __forceinline__ void cvt_rows(const float* __restrict__ src, bf16_t* __restrict__ dst, size_t n4, size_t gtid, size_t gn) {
;     ...
; #pragma unroll
;     for (int q = 0; q < 4; ++q) {
;       const size_t i = i0 + q * gn;
;       if (i < n4) { u32x2 w; w[0] = cvt_pk_bf16(v[q][0], v[q][1]); w[1] = cvt_pk_bf16(v[q][2], v[q][3]); *(u32x2*)(dst + i * 4) = w; }
;     }
.LBB0_2233:
	v_cvt_pk_bf16_f32 v2, v2, v3
	v_cvt_pk_bf16_f32 v3, v4, v5
	v_lshl_add_u64 v[4:5], s[40:41], 0, v[22:23]
	global_store_dwordx2 v[4:5], v[2:3], off sc1
	s_or_b64 exec, exec, s[42:43]
	s_and_saveexec_b64 s[0:1], s[2:3]
	s_cbranch_execz .LBB0_2222
.LBB0_2234:
	v_lshl_add_u64 v[4:5], s[40:41], 0, v[24:25]
	v_cvt_pk_bf16_f32 v2, v14, v15
	v_cvt_pk_bf16_f32 v3, v16, v17
	global_store_dwordx2 v[4:5], v[2:3], off sc1
	s_branch .LBB0_2222

; __device__ __forceinline__ void cvt_rows(const float* __restrict__ src, bf16_t* __restrict__ dst, size_t n4, size_t gtid, size_t gn) {
;     ...
; #pragma unroll
;     for (int q = 0; q < 4; ++q) {
;       const size_t i = i0 + q * gn;
;       if (i < n4) { u32x2 w; w[0] = cvt_pk_bf16(v[q][0], v[q][1]); w[1] = cvt_pk_bf16(v[q][2], v[q][3]); *(u32x2*)(dst + i * 4) = w; }
;     }
.LBB0_2244:
	s_or_b64 exec, exec, s[46:47]
	s_waitcnt vmcnt(0)
	v_cvt_pk_bf16_f32 v10, v10, v11
	v_cvt_pk_bf16_f32 v11, v12, v13
	v_lshl_add_u64 v[12:13], s[44:45], 0, v[20:21]
	global_store_dwordx2 v[12:13], v[10:11], off sc1
	s_and_saveexec_b64 s[46:47], s[0:1]
	s_cbranch_execz .LBB0_2247
	v_cvt_pk_bf16_f32 v6, v6, v7
	v_cvt_pk_bf16_f32 v7, v8, v9
	v_lshl_add_u64 v[8:9], s[44:45], 0, v[26:27]
	global_store_dwordx2 v[8:9], v[6:7], off sc1
	s_or_b64 exec, exec, s[46:47]
	s_and_saveexec_b64 s[0:1], s[2:3]
	s_cbranch_execnz .LBB0_2248

; __device__ __forceinline__ void cvt_rows(const float* __restrict__ src, bf16_t* __restrict__ dst, size_t n4, size_t gtid, size_t gn) {
;     ...
; #pragma unroll
;     for (int q = 0; q < 4; ++q) {
;       const size_t i = i0 + q * gn;
;       if (i < n4) { u32x2 w; w[0] = cvt_pk_bf16(v[q][0], v[q][1]); w[1] = cvt_pk_bf16(v[q][2], v[q][3]); *(u32x2*)(dst + i * 4) = w; }
;     }
.LBB0_2248:
	v_cvt_pk_bf16_f32 v2, v2, v3
	v_cvt_pk_bf16_f32 v3, v4, v5
	v_lshl_add_u64 v[4:5], s[44:45], 0, v[22:23]
	global_store_dwordx2 v[4:5], v[2:3], off sc1
	s_or_b64 exec, exec, s[0:1]
	s_and_saveexec_b64 s[0:1], s[4:5]
	s_cbranch_execz .LBB0_2237
.LBB0_2249:
	v_lshl_add_u64 v[4:5], s[44:45], 0, v[24:25]
	v_cvt_pk_bf16_f32 v2, v14, v15
	v_cvt_pk_bf16_f32 v3, v16, v17
	global_store_dwordx2 v[4:5], v[2:3], off sc1
	s_branch .LBB0_2237

; __device__ __forceinline__ void phase_prep(KP kp, unsigned char* shm) {
;     ...
;   for (size_t i = gtid; i < (size_t)MS * 256; i += gn)
;     *(f32x4*)(kp->out + O_Y + (size_t)MP * 1024 + i * 4) = *(const f32x4*)(kp->x_sample + i * 4) * ALPHA;
.LBB0_2251:
	v_lshl_add_u64 v[4:5], s[14:15], 0, v[18:19]
	global_load_dwordx4 v[4:7], v[4:5], off
	v_lshl_add_u64 v[2:3], v[2:3], 0, s[8:9]
	v_cmp_lt_u64_e64 s[0:1], s[16:17], v[2:3]
	v_lshl_add_u64 v[8:9], s[26:27], 0, v[18:19]
	v_lshl_add_u64 v[18:19], v[18:19], 0, s[24:25]
	s_or_b64 s[2:3], s[0:1], s[2:3]
	s_waitcnt vmcnt(0)
	v_pk_mul_f32 v[4:5], v[4:5], s[4:5] op_sel_hi:[1,0]
	v_pk_mul_f32 v[6:7], v[6:7], s[4:5] op_sel_hi:[1,0]
	global_store_dwordx4 v[8:9], v[4:7], off sc1
	s_andn2_b64 exec, exec, s[2:3]
	s_cbranch_execnz .LBB0_2251

; __device__ __forceinline__ void phase_prep(KP kp, unsigned char* shm) {
;     ...
; #pragma unroll
;     for (int q = 0; q < 4; ++q) {
;       const size_t i = i0 + q * gn;
;       if (i < 2ull * 16 * 2048 * 32) {
;         const size_t row = i >> 5, c4 = i & 31, lsb = row >> 11, rr = row & 2047;
;         const size_t d = (lsb * 2080 + rr) * 128 + c4 * 4;
;         u32x2 w;
;         w[0] = cvt_pk_bf16(a[q][0], a[q][1]); w[1] = cvt_pk_bf16(a[q][2], a[q][3]);
;         *(u32x2*)((bf16_t*)(ws + W_KS) + d) = w;
;         w[0] = cvt_pk_bf16(b[q][0], b[q][1]); w[1] = cvt_pk_bf16(b[q][2], b[q][3]);
;         *(u32x2*)((bf16_t*)(ws + W_VS) + d) = w;
;       }
;     }
.LBB0_2261:
	s_or_b64 exec, exec, s[6:7]
	v_bfe_u32 v56, v60, 5, 11
	v_alignbit_b32 v60, v61, v60, 16
	v_mad_u64_u32 v[66:67], s[6:7], v60, s40, v[56:57]
	v_lshrrev_b32_e32 v56, 16, v61
	v_mad_u32_u24 v67, v56, s40, v67
	v_and_b32_e32 v1, 0x7c, v38
	s_waitcnt vmcnt(1)
	v_cvt_pk_bf16_f32 v14, v14, v15
	v_cvt_pk_bf16_f32 v15, v16, v17
	v_lshlrev_b64 v[16:17], 8, v[66:67]
	v_lshl_or_b32 v16, v1, 1, v16
	v_lshl_add_u64 v[60:61], s[16:17], 0, v[16:17]
	global_store_dwordx2 v[60:61], v[14:15], off sc1
	s_waitcnt vmcnt(1)
	v_cvt_pk_bf16_f32 v2, v2, v3
	v_cvt_pk_bf16_f32 v3, v4, v5
	v_lshl_add_u64 v[4:5], s[24:25], 0, v[16:17]
	global_store_dwordx2 v[4:5], v[2:3], off sc1
	s_and_saveexec_b64 s[6:7], s[0:1]
	s_cbranch_execz .LBB0_2264
	v_bfe_u32 v56, v58, 5, 11
	v_alignbit_b32 v2, v59, v58, 16
	v_mad_u64_u32 v[2:3], s[0:1], v2, s40, v[56:57]
	v_lshrrev_b32_e32 v4, 16, v59
	v_mad_u32_u24 v3, v4, s40, v3
	v_lshlrev_b64 v[2:3], 8, v[2:3]
	v_lshl_or_b32 v2, v1, 1, v2
	v_cvt_pk_bf16_f32 v4, v10, v11
	v_cvt_pk_bf16_f32 v5, v12, v13
	v_lshl_add_u64 v[10:11], s[16:17], 0, v[2:3]
	v_lshl_add_u64 v[2:3], s[24:25], 0, v[2:3]
	global_store_dwordx2 v[10:11], v[4:5], off sc1
	v_cvt_pk_bf16_f32 v4, v6, v7
	v_cvt_pk_bf16_f32 v5, v8, v9
	global_store_dwordx2 v[2:3], v[4:5], off sc1
	s_or_b64 exec, exec, s[6:7]
	s_and_saveexec_b64 s[0:1], s[2:3]
	s_cbranch_execnz .LBB0_2265

; __device__ __forceinline__ void phase_prep(KP kp, unsigned char* shm) {
;     ...
; #pragma unroll
;     for (int q = 0; q < 4; ++q) {
;       const size_t i = i0 + q * gn;
;       if (i < 2ull * 16 * 2048 * 32) {
;         const size_t row = i >> 5, c4 = i & 31, lsb = row >> 11, rr = row & 2047;
;         const size_t d = (lsb * 2080 + rr) * 128 + c4 * 4;
;         u32x2 w;
;         w[0] = cvt_pk_bf16(a[q][0], a[q][1]); w[1] = cvt_pk_bf16(a[q][2], a[q][3]);
;         *(u32x2*)((bf16_t*)(ws + W_KS) + d) = w;
;         w[0] = cvt_pk_bf16(b[q][0], b[q][1]); w[1] = cvt_pk_bf16(b[q][2], b[q][3]);
;         *(u32x2*)((bf16_t*)(ws + W_VS) + d) = w;
;       }
;     }
.LBB0_2265:
	v_bfe_u32 v56, v62, 5, 11
	v_alignbit_b32 v2, v63, v62, 16
	v_mad_u64_u32 v[2:3], s[2:3], v2, s40, v[56:57]
	v_lshrrev_b32_e32 v4, 16, v63
	v_mad_u32_u24 v3, v4, s40, v3
	v_lshlrev_b64 v[2:3], 8, v[2:3]
	v_lshl_or_b32 v2, v1, 1, v2
	v_cvt_pk_bf16_f32 v4, v22, v23
	v_cvt_pk_bf16_f32 v5, v24, v25
	v_lshl_add_u64 v[6:7], s[16:17], 0, v[2:3]
	v_lshl_add_u64 v[2:3], s[24:25], 0, v[2:3]
	global_store_dwordx2 v[6:7], v[4:5], off sc1
	v_cvt_pk_bf16_f32 v4, v18, v19
	v_cvt_pk_bf16_f32 v5, v20, v21
	global_store_dwordx2 v[2:3], v[4:5], off sc1
	s_or_b64 exec, exec, s[0:1]
	s_and_saveexec_b64 s[0:1], s[4:5]
	s_cbranch_execz .LBB0_2254
.LBB0_2266:
	v_bfe_u32 v56, v64, 5, 11
	v_alignbit_b32 v2, v65, v64, 16
	v_mad_u64_u32 v[2:3], s[2:3], v2, s40, v[56:57]
	v_lshrrev_b32_e32 v4, 16, v65
	v_mad_u32_u24 v3, v4, s40, v3
	v_lshlrev_b64 v[2:3], 8, v[2:3]
	v_lshl_or_b32 v2, v1, 1, v2
	v_cvt_pk_bf16_f32 v4, v30, v31
	v_cvt_pk_bf16_f32 v5, v32, v33
	v_lshl_add_u64 v[6:7], s[16:17], 0, v[2:3]
	v_lshl_add_u64 v[2:3], s[24:25], 0, v[2:3]
	global_store_dwordx2 v[6:7], v[4:5], off sc1
	v_cvt_pk_bf16_f32 v4, v26, v27
	v_cvt_pk_bf16_f32 v5, v28, v29
	global_store_dwordx2 v[2:3], v[4:5], off sc1
	s_branch .LBB0_2254

; __device__ __forceinline__ size_t kif_off(int key, int li  ) { return ((size_t)(((key >> 5) * 4 + (li >> 2)) * 64 + ((li >> 1) & 1) * 32 + (key & 31))) * 8 + (li & 1) * 4; }
; __device__ __forceinline__ void phase_prep(KP kp, unsigned char* shm) {
;     ...
;     for (int q = 0; q < 4; ++q) {
;       const size_t i = i0 + q * gn;
;       if (i < 2ull * 16 * 2048 * 16) {
;         const size_t row = i >> 4, c4 = i & 15, lsb = row >> 11, rr = row & 2047;
;         u32x2 w;
;         w[0] = cvt_pk_bf16(a[q][0], a[q][1]); w[1] = cvt_pk_bf16(a[q][2], a[q][3]);
;         *(u32x2*)((bf16_t*)(ws + W_KIS) + lsb * 2080 * 64 + kif_off((int)rr, (int)c4)) = w;
;       }
;     }
.LBB0_2276:
	s_or_b64 exec, exec, s[44:45]
	s_waitcnt vmcnt(0)
	v_cvt_pk_bf16_f32 v40, v14, v15
	v_cvt_pk_bf16_f32 v41, v16, v17
	v_alignbit_b32 v16, v33, v32, 15
	v_mov_b64_e32 v[14:15], s[14:15]
	v_mad_u64_u32 v[14:15], s[44:45], v16, s33, v[14:15]
	v_lshrrev_b32_e32 v16, 15, v33
	v_bfe_u32 v1, v32, 2, 2
	v_mad_u32_u24 v15, v16, s33, v15
	v_lshrrev_b32_e32 v16, 7, v32
	v_and_or_b32 v16, v16, s46, v1
	v_lshlrev_b32_e32 v16, 10, v16
	v_mov_b32_e32 v17, v25
	v_and_b32_e32 v24, 0x200, v20
	v_lshl_add_u64 v[14:15], v[14:15], 0, v[16:17]
	v_and_b32_e32 v38, 0x1f0, v32
	v_mov_b32_e32 v39, v25
	v_and_b32_e32 v42, 4, v18
	v_lshl_add_u64 v[14:15], v[14:15], 0, v[24:25]
	v_lshl_add_u64 v[16:17], v[14:15], 0, v[38:39]
	v_lshlrev_b32_e32 v14, 1, v42
	v_mov_b32_e32 v15, v25
	v_lshl_add_u64 v[16:17], v[16:17], 0, v[14:15]
	global_store_dwordx2 v[16:17], v[40:41], off sc1
	s_and_saveexec_b64 s[44:45], s[4:5]
	s_cbranch_execz .LBB0_2279
	v_cvt_pk_bf16_f32 v10, v10, v11
	v_cvt_pk_bf16_f32 v11, v12, v13
	v_alignbit_b32 v16, v27, v26, 15
	v_mov_b64_e32 v[12:13], s[14:15]
	v_mad_u64_u32 v[12:13], s[4:5], v16, s33, v[12:13]
	v_lshrrev_b32_e32 v16, 15, v27
	v_mad_u32_u24 v13, v16, s33, v13
	v_lshrrev_b32_e32 v16, 7, v26
	v_and_or_b32 v16, v16, s46, v1
	v_lshlrev_b32_e32 v16, 10, v16
	v_mov_b32_e32 v17, v25
	v_lshl_add_u64 v[12:13], v[12:13], 0, v[16:17]
	v_lshl_add_u64 v[12:13], v[12:13], 0, v[24:25]
	v_lshl_add_u64 v[12:13], v[12:13], 0, v[38:39]
	v_lshl_add_u64 v[12:13], v[12:13], 0, v[14:15]
	global_store_dwordx2 v[12:13], v[10:11], off sc1
	s_or_b64 exec, exec, s[44:45]
	s_and_saveexec_b64 s[4:5], s[2:3]
	s_cbranch_execnz .LBB0_2280

; __device__ __forceinline__ size_t kif_off(int key, int li  ) { return ((size_t)(((key >> 5) * 4 + (li >> 2)) * 64 + ((li >> 1) & 1) * 32 + (key & 31))) * 8 + (li & 1) * 4; }
; __device__ __forceinline__ void phase_prep(KP kp, unsigned char* shm) {
;     ...
;     for (int q = 0; q < 4; ++q) {
;       const size_t i = i0 + q * gn;
;       if (i < 2ull * 16 * 2048 * 16) {
;         const size_t row = i >> 4, c4 = i & 15, lsb = row >> 11, rr = row & 2047;
;         u32x2 w;
;         w[0] = cvt_pk_bf16(a[q][0], a[q][1]); w[1] = cvt_pk_bf16(a[q][2], a[q][3]);
;         *(u32x2*)((bf16_t*)(ws + W_KIS) + lsb * 2080 * 64 + kif_off((int)rr, (int)c4)) = w;
;       }
;     }
.LBB0_2280:
	v_cvt_pk_bf16_f32 v6, v6, v7
	v_cvt_pk_bf16_f32 v7, v8, v9
	v_alignbit_b32 v10, v31, v30, 15
	v_mov_b64_e32 v[8:9], s[14:15]
	v_mad_u64_u32 v[8:9], s[2:3], v10, s33, v[8:9]
	v_lshrrev_b32_e32 v10, 15, v31
	v_mad_u32_u24 v9, v10, s33, v9
	v_lshrrev_b32_e32 v10, 7, v30
	v_and_or_b32 v10, v10, s46, v1
	v_lshlrev_b32_e32 v10, 10, v10
	v_mov_b32_e32 v11, v25
	v_lshl_add_u64 v[8:9], v[8:9], 0, v[10:11]
	v_lshl_add_u64 v[8:9], v[8:9], 0, v[24:25]
	v_lshl_add_u64 v[8:9], v[8:9], 0, v[38:39]
	v_mov_b32_e32 v15, v25
	v_lshl_add_u64 v[8:9], v[8:9], 0, v[14:15]
	global_store_dwordx2 v[8:9], v[6:7], off sc1
	s_or_b64 exec, exec, s[4:5]
	s_and_saveexec_b64 s[2:3], s[0:1]
	s_cbranch_execz .LBB0_2269
.LBB0_2281:
	v_cvt_pk_bf16_f32 v2, v2, v3
	v_cvt_pk_bf16_f32 v3, v4, v5
	v_alignbit_b32 v6, v29, v28, 15
	v_mov_b64_e32 v[4:5], s[14:15]
	v_mad_u64_u32 v[4:5], s[0:1], v6, s33, v[4:5]
	v_lshrrev_b32_e32 v6, 15, v29
	v_mad_u32_u24 v5, v6, s33, v5
	v_lshrrev_b32_e32 v6, 7, v28
	v_and_or_b32 v1, v6, s46, v1
	v_lshlrev_b32_e32 v6, 10, v1
	v_mov_b32_e32 v7, v25
	v_lshl_add_u64 v[4:5], v[4:5], 0, v[6:7]
	v_lshl_add_u64 v[4:5], v[4:5], 0, v[24:25]
	v_lshl_add_u64 v[4:5], v[4:5], 0, v[38:39]
	v_mov_b32_e32 v15, v25
	v_lshl_add_u64 v[4:5], v[4:5], 0, v[14:15]
	global_store_dwordx2 v[4:5], v[2:3], off sc1
	s_branch .LBB0_2269

; __device__ __forceinline__ void phase_prep(KP kp, unsigned char* shm) {
;     ...
;   for (size_t i = gtid; i < 4096 * 8; i += gn) {
;     const int pos = (int)(i >> 3), fi = (int)(i & 7);
;     const float fr[8] = {1.0f, 0.1939227432012558f, 0.03760603070259094f, 0.007292664609849453f, 0.0014142135623842478f, 0.00027424818836152554f,
;                          5.3182957344688475e-05f, 1.0313385246263351e-05f};
;     float f = fr[0];
; #pragma unroll
;     for (int q = 1; q < 8; ++q) f = (fi == q) ? fr[q] : f;
;     const float ang = (float)pos * f;
;     double rev = (double)ang * 0.15915494309189535;
;     rev -= floor(rev);
;     const float t = (float)rev;
;     float* d = (float*)(ws + W_ROPE) + i * 2;
;     d[0] = __builtin_amdgcn_cosf(t);
;     d[1] = __builtin_amdgcn_sinf(t);
;   }
.LBB0_2284:
	v_lshrrev_b64 v[6:7], 3, v[4:5]
	v_ffbh_u32_e32 v8, v7
	v_min_u32_e32 v8, 32, v8
	v_lshlrev_b64 v[6:7], v8, v[6:7]
	v_min_u32_e32 v6, 1, v6
	v_or_b32_e32 v6, v7, v6
	v_cvt_f32_u32_e32 v6, v6
	v_sub_u32_e32 v7, 32, v8
	v_lshl_add_u64 v[4:5], v[4:5], 0, s[8:9]
	v_cmp_lt_u64_e64 s[0:1], s[12:13], v[4:5]
	v_ldexp_f32 v6, v6, v7
	v_mul_f32_e32 v6, v1, v6
	v_cvt_f64_f32_e32 v[6:7], v6
	v_mul_f64 v[8:9], v[6:7], s[10:11]
	v_floor_f64_e32 v[8:9], v[8:9]
	v_fma_f64 v[6:7], v[6:7], s[10:11], -v[8:9]
	v_cvt_f32_f64_e32 v7, v[6:7]
	v_cos_f32_e32 v6, v7
	v_sin_f32_e32 v7, v7
	s_or_b64 s[6:7], s[0:1], s[6:7]
	global_store_dwordx2 v[2:3], v[6:7], off offset:-4 sc1
	v_lshl_add_u64 v[2:3], v[2:3], 0, s[4:5]
	s_andn2_b64 exec, exec, s[6:7]
	s_cbranch_execnz .LBB0_2284

; __device__ __forceinline__ void phase_prep(KP kp, unsigned char* shm) {
;     ...
;   for (size_t i = gtid; i < 2ull * 4 * 128 * 128; i += gn) {
;     const int s = (int)(i & 127), t = (int)((i >> 7) & 127);
;     const float v = s <= t ? kp->w_s[i] : 0.f;
;     ((bf16_t*)(ws + W_WSM))[i] = (bf16_t)(cvt_pk_bf16(v, 0.f) & 0xffffu);
;   }
.LBB0_2287:
	s_or_b64 exec, exec, s[12:13]
	v_lshl_add_u64 v[36:37], v[36:37], 0, s[8:9]
	v_cmp_lt_u64_e32 vcc, s[10:11], v[36:37]
	s_waitcnt vmcnt(0)
	v_cvt_pk_bf16_f32 v7, v7, v6
	global_store_short v[2:3], v7, off sc1
	v_lshl_add_u64 v[2:3], v[2:3], 0, s[2:3]
	s_or_b64 s[6:7], vcc, s[6:7]
	v_lshl_add_u64 v[4:5], v[4:5], 0, s[4:5]
	s_andn2_b64 exec, exec, s[6:7]
	s_cbranch_execz .LBB0_2290

; __device__ __forceinline__ void phase_attn(KP kp, int l, unsigned char* shm) {
;     ...
;       float mx = -1e30f;
; #pragma unroll
;       for (int kb = 0; kb < 16; ++kb)
; #pragma unroll
;         for (int j = 0; j < 4; ++j) {
;           const int key = kb * 16 + kg * 4 + j;
;           lg[kb][j] = key < cnt ? lg[kb][j] : -1e30f;
;           mx = fmaxf(mx, lg[kb][j]);
;         }
;       mx = fmaxf(mx, __shfl_xor(mx, 16));
;       mx = fmaxf(mx, __shfl_xor(mx, 32));
;       float sum = 0.f;
; #pragma unroll
;       for (int kb = 0; kb < 16; ++kb)
; #pragma unroll
;         for (int j = 0; j < 4; ++j) { lg[kb][j] = __builtin_amdgcn_exp2f(lg[kb][j] - mx); sum += lg[kb][j]; }
;       sum += __shfl_xor(sum, 16);
;       sum += __shfl_xor(sum, 32);
;       const float inv = 1.f / sum;
.Lattn_nomask_4:
	v_max3_f32 v176, v32, v33, v34
	v_max3_f32 v176, v176, v35, v36
	v_max3_f32 v176, v176, v37, v38
	v_max3_f32 v176, v176, v39, v40
	v_max3_f32 v176, v176, v41, v42
	v_max3_f32 v176, v176, v43, v44
	v_max3_f32 v176, v176, v45, v46
	v_max3_f32 v176, v176, v47, v48
	v_max3_f32 v176, v176, v49, v50
	v_max3_f32 v176, v176, v51, v52
	v_max3_f32 v176, v176, v53, v54
	v_max3_f32 v176, v176, v55, v56
	v_max3_f32 v176, v176, v57, v58
	v_max3_f32 v176, v176, v59, v60
	v_max3_f32 v176, v176, v61, v62
	v_max3_f32 v176, v176, v63, v64
	v_max3_f32 v176, v176, v65, v66
	v_max3_f32 v176, v176, v67, v68
	v_max3_f32 v176, v176, v69, v70
	v_max3_f32 v176, v176, v71, v72
	v_max3_f32 v176, v176, v73, v74
	v_max3_f32 v176, v176, v75, v76
	v_max3_f32 v176, v176, v77, v78
	v_max3_f32 v176, v176, v79, v80
	v_max3_f32 v176, v176, v81, v82
	v_max3_f32 v176, v176, v83, v84
	v_max3_f32 v176, v176, v85, v86
	v_max3_f32 v176, v176, v87, v88
	v_max3_f32 v176, v176, v89, v90
	v_max3_f32 v176, v176, v91, v92
	v_max3_f32 v176, v176, v93, v94
	v_max_f32_e32 v176, v176, v95
	ds_bpermute_b32 v197, v191, v176
	s_waitcnt lgkmcnt(0)
	v_max_f32_e32 v176, v176, v197
	ds_bpermute_b32 v197, v192, v176
	s_waitcnt lgkmcnt(0)
	v_max_f32_e32 v176, v176, v197
	v_mov_b32_e32 v177, v176
	v_pk_add_f32 v[32:33], v[32:33], v[176:177] neg_lo:[0,1] neg_hi:[0,1]
	v_pk_add_f32 v[34:35], v[34:35], v[176:177] neg_lo:[0,1] neg_hi:[0,1]
	v_pk_add_f32 v[36:37], v[36:37], v[176:177] neg_lo:[0,1] neg_hi:[0,1]
	v_pk_add_f32 v[38:39], v[38:39], v[176:177] neg_lo:[0,1] neg_hi:[0,1]
	v_pk_add_f32 v[40:41], v[40:41], v[176:177] neg_lo:[0,1] neg_hi:[0,1]
	v_pk_add_f32 v[42:43], v[42:43], v[176:177] neg_lo:[0,1] neg_hi:[0,1]
	v_pk_add_f32 v[44:45], v[44:45], v[176:177] neg_lo:[0,1] neg_hi:[0,1]
	v_pk_add_f32 v[46:47], v[46:47], v[176:177] neg_lo:[0,1] neg_hi:[0,1]
	v_pk_add_f32 v[48:49], v[48:49], v[176:177] neg_lo:[0,1] neg_hi:[0,1]
	v_pk_add_f32 v[50:51], v[50:51], v[176:177] neg_lo:[0,1] neg_hi:[0,1]
	v_pk_add_f32 v[52:53], v[52:53], v[176:177] neg_lo:[0,1] neg_hi:[0,1]
	v_pk_add_f32 v[54:55], v[54:55], v[176:177] neg_lo:[0,1] neg_hi:[0,1]
	v_pk_add_f32 v[56:57], v[56:57], v[176:177] neg_lo:[0,1] neg_hi:[0,1]
	v_pk_add_f32 v[58:59], v[58:59], v[176:177] neg_lo:[0,1] neg_hi:[0,1]
	v_pk_add_f32 v[60:61], v[60:61], v[176:177] neg_lo:[0,1] neg_hi:[0,1]
	v_pk_add_f32 v[62:63], v[62:63], v[176:177] neg_lo:[0,1] neg_hi:[0,1]
	v_pk_add_f32 v[64:65], v[64:65], v[176:177] neg_lo:[0,1] neg_hi:[0,1]
	v_pk_add_f32 v[66:67], v[66:67], v[176:177] neg_lo:[0,1] neg_hi:[0,1]
	v_pk_add_f32 v[68:69], v[68:69], v[176:177] neg_lo:[0,1] neg_hi:[0,1]
	v_pk_add_f32 v[70:71], v[70:71], v[176:177] neg_lo:[0,1] neg_hi:[0,1]
	v_pk_add_f32 v[72:73], v[72:73], v[176:177] neg_lo:[0,1] neg_hi:[0,1]
	v_pk_add_f32 v[74:75], v[74:75], v[176:177] neg_lo:[0,1] neg_hi:[0,1]
	v_pk_add_f32 v[76:77], v[76:77], v[176:177] neg_lo:[0,1] neg_hi:[0,1]
	v_pk_add_f32 v[78:79], v[78:79], v[176:177] neg_lo:[0,1] neg_hi:[0,1]
	v_pk_add_f32 v[80:81], v[80:81], v[176:177] neg_lo:[0,1] neg_hi:[0,1]
	v_pk_add_f32 v[82:83], v[82:83], v[176:177] neg_lo:[0,1] neg_hi:[0,1]
	v_pk_add_f32 v[84:85], v[84:85], v[176:177] neg_lo:[0,1] neg_hi:[0,1]
	v_pk_add_f32 v[86:87], v[86:87], v[176:177] neg_lo:[0,1] neg_hi:[0,1]
	v_pk_add_f32 v[88:89], v[88:89], v[176:177] neg_lo:[0,1] neg_hi:[0,1]
	v_pk_add_f32 v[90:91], v[90:91], v[176:177] neg_lo:[0,1] neg_hi:[0,1]
	v_pk_add_f32 v[92:93], v[92:93], v[176:177] neg_lo:[0,1] neg_hi:[0,1]
	v_pk_add_f32 v[94:95], v[94:95], v[176:177] neg_lo:[0,1] neg_hi:[0,1]
	v_exp_f32_e32 v32, v32
	v_exp_f32_e32 v33, v33
	v_exp_f32_e32 v34, v34
	v_exp_f32_e32 v35, v35
	v_exp_f32_e32 v36, v36
	v_exp_f32_e32 v37, v37
	v_pk_add_f32 v[178:179], v[32:33], v[34:35]
	v_exp_f32_e32 v38, v38
	v_exp_f32_e32 v39, v39
	v_pk_add_f32 v[178:179], v[178:179], v[36:37]
	v_exp_f32_e32 v40, v40
	v_exp_f32_e32 v41, v41
	v_pk_add_f32 v[178:179], v[178:179], v[38:39]
	v_exp_f32_e32 v42, v42
	v_exp_f32_e32 v43, v43
	v_pk_add_f32 v[178:179], v[178:179], v[40:41]
	v_exp_f32_e32 v44, v44
	v_exp_f32_e32 v45, v45
	v_pk_add_f32 v[178:179], v[178:179], v[42:43]
	v_exp_f32_e32 v46, v46
	v_exp_f32_e32 v47, v47
	v_pk_add_f32 v[178:179], v[178:179], v[44:45]
	v_exp_f32_e32 v48, v48
	v_exp_f32_e32 v49, v49
	v_pk_add_f32 v[178:179], v[178:179], v[46:47]
	v_exp_f32_e32 v50, v50
	v_exp_f32_e32 v51, v51
	v_pk_add_f32 v[178:179], v[178:179], v[48:49]
	v_exp_f32_e32 v52, v52
	v_exp_f32_e32 v53, v53
	v_pk_add_f32 v[178:179], v[178:179], v[50:51]
	v_exp_f32_e32 v54, v54
	v_exp_f32_e32 v55, v55
	v_pk_add_f32 v[178:179], v[178:179], v[52:53]
	v_exp_f32_e32 v56, v56
	v_exp_f32_e32 v57, v57
	v_pk_add_f32 v[178:179], v[178:179], v[54:55]
	v_exp_f32_e32 v58, v58
	v_exp_f32_e32 v59, v59
	v_pk_add_f32 v[178:179], v[178:179], v[56:57]
	v_exp_f32_e32 v60, v60
	v_exp_f32_e32 v61, v61
	v_pk_add_f32 v[178:179], v[178:179], v[58:59]
	v_exp_f32_e32 v62, v62
	v_exp_f32_e32 v63, v63
	v_pk_add_f32 v[178:179], v[178:179], v[60:61]
	v_exp_f32_e32 v64, v64
	v_exp_f32_e32 v65, v65
	v_pk_add_f32 v[178:179], v[178:179], v[62:63]
	v_exp_f32_e32 v66, v66
	v_exp_f32_e32 v67, v67
	v_pk_add_f32 v[178:179], v[178:179], v[64:65]
	v_exp_f32_e32 v68, v68
	v_exp_f32_e32 v69, v69
	v_pk_add_f32 v[178:179], v[178:179], v[66:67]
	v_exp_f32_e32 v70, v70
	v_exp_f32_e32 v71, v71
	v_pk_add_f32 v[178:179], v[178:179], v[68:69]
	v_exp_f32_e32 v72, v72
	v_exp_f32_e32 v73, v73
	v_pk_add_f32 v[178:179], v[178:179], v[70:71]
	v_exp_f32_e32 v74, v74
	v_exp_f32_e32 v75, v75
	v_pk_add_f32 v[178:179], v[178:179], v[72:73]
	v_exp_f32_e32 v76, v76
	v_exp_f32_e32 v77, v77
	v_pk_add_f32 v[178:179], v[178:179], v[74:75]
; __device__ __forceinline__ void phase_attn(KP kp, int l, unsigned char* shm) {
;     ...
;         for (int j = 0; j < 4; ++j) { lg[kb][j] = __builtin_amdgcn_exp2f(lg[kb][j] - mx); sum += lg[kb][j]; }
;       sum += __shfl_xor(sum, 16);
;       sum += __shfl_xor(sum, 32);
;       const float inv = 1.f / sum;
;       bf16x8 pf[8];
; #pragma unroll
;       for (int s8 = 0; s8 < 8; ++s8) {
;         u32x4 pk;
;         pk[0] = cvt_pk_bf16(lg[2 * s8][0], lg[2 * s8][1]);
;         pk[1] = cvt_pk_bf16(lg[2 * s8][2], lg[2 * s8][3]);
;         pk[2] = cvt_pk_bf16(lg[2 * s8 + 1][0], lg[2 * s8 + 1][1]);
;         pk[3] = cvt_pk_bf16(lg[2 * s8 + 1][2], lg[2 * s8 + 1][3]);
;         pf[s8] = __builtin_bit_cast(bf16x8, pk);
;       }
;       f32x4 oacc[4];
; #pragma unroll
;       for (int c = 0; c < 4; ++c) oacc[c] = (f32x4){0.f, 0.f, 0.f, 0.f};
;       for (int repV = 0; repV < ((PROBE & 256) ? 2 : 1); ++repV)
;       {
;         if (repV) {
; #pragma unroll
;           for (int c = 0; c < 4; ++c) oacc[c] = (f32x4){0.f, 0.f, 0.f, 0.f};
;         }
; #pragma unroll
;         for (int i = 16; i < 32; ++i) {
;           const int idx = selw[i * 8 + ks8];
;           vr[i] = *(const u32x4*)(vbase + (size_t)idx * 128 + kvh * 64 + dc * 8);
;         }
; #pragma unroll
;         for (int s8 = 0; s8 < 8; ++s8) {
; #pragma unroll
;           for (int it = 0; it < 4; ++it) *(u32x4*)(tileb + (it * 8 + ks8) * 144 + dc * 16) = vr[s8 * 4 + it];
;           u32x2 t0, t1, t2, t3, t4, t5, t6, t7;
;           asm volatile(
;               "ds_read_b64_tr_b16 %0, %8\n\tds_read_b64_tr_b16 %1, %8 offset:2304\n\t"
;               "ds_read_b64_tr_b16 %2, %8 offset:32\n\tds_read_b64_tr_b16 %3, %8 offset:2336\n\t"
;               "ds_read_b64_tr_b16 %4, %8 offset:64\n\tds_read_b64_tr_b16 %5, %8 offset:2368\n\t"
;               "ds_read_b64_tr_b16 %6, %8 offset:96\n\tds_read_b64_tr_b16 %7, %8 offset:2400\n\t"
;               "s_waitcnt lgkmcnt(0)"
;               : "=&v"(t0), "=&v"(t1), "=&v"(t2), "=&v"(t3), "=&v"(t4), "=&v"(t5), "=&v"(t6), "=&v"(t7)
;               : "v"(tr_addr)
;               : "memory");
;           const bf16x8 a0 = __builtin_bit_cast(bf16x8, (u32x4){t0[0], t0[1], t1[0], t1[1]});
;           const bf16x8 a1 = __builtin_bit_cast(bf16x8, (u32x4){t2[0], t2[1], t3[0], t3[1]});
;           const bf16x8 a2 = __builtin_bit_cast(bf16x8, (u32x4){t4[0], t4[1], t5[0], t5[1]});
	v_exp_f32_e32 v78, v78
	v_exp_f32_e32 v79, v79
	v_pk_add_f32 v[178:179], v[178:179], v[76:77]
	v_exp_f32_e32 v80, v80
	v_exp_f32_e32 v81, v81
	v_pk_add_f32 v[178:179], v[178:179], v[78:79]
	v_exp_f32_e32 v82, v82
	v_exp_f32_e32 v83, v83
	v_pk_add_f32 v[178:179], v[178:179], v[80:81]
	v_exp_f32_e32 v84, v84
	v_exp_f32_e32 v85, v85
	v_pk_add_f32 v[178:179], v[178:179], v[82:83]
	v_exp_f32_e32 v86, v86
	v_exp_f32_e32 v87, v87
	v_pk_add_f32 v[178:179], v[178:179], v[84:85]
	v_exp_f32_e32 v88, v88
	v_exp_f32_e32 v89, v89
	v_pk_add_f32 v[178:179], v[178:179], v[86:87]
	v_exp_f32_e32 v90, v90
	v_exp_f32_e32 v91, v91
	v_pk_add_f32 v[178:179], v[178:179], v[88:89]
	v_exp_f32_e32 v92, v92
	v_exp_f32_e32 v93, v93
	v_pk_add_f32 v[178:179], v[178:179], v[90:91]
	v_exp_f32_e32 v94, v94
	v_exp_f32_e32 v95, v95
	v_pk_add_f32 v[178:179], v[178:179], v[92:93]
	s_nop 0
	v_pk_add_f32 v[178:179], v[178:179], v[94:95]
	v_add_f32_e32 v210, v178, v179
	ds_bpermute_b32 v197, v191, v210
	v_cvt_pk_bf16_f32 v96, v32, v33
	v_cvt_pk_bf16_f32 v97, v34, v35
	v_cvt_pk_bf16_f32 v98, v36, v37
	v_cvt_pk_bf16_f32 v99, v38, v39
	v_cvt_pk_bf16_f32 v100, v40, v41
	v_cvt_pk_bf16_f32 v101, v42, v43
	v_cvt_pk_bf16_f32 v102, v44, v45
	v_cvt_pk_bf16_f32 v103, v46, v47
	v_cvt_pk_bf16_f32 v104, v48, v49
	v_cvt_pk_bf16_f32 v105, v50, v51
	v_cvt_pk_bf16_f32 v106, v52, v53
	v_cvt_pk_bf16_f32 v107, v54, v55
	v_cvt_pk_bf16_f32 v108, v56, v57
	v_cvt_pk_bf16_f32 v109, v58, v59
	v_cvt_pk_bf16_f32 v110, v60, v61
	v_cvt_pk_bf16_f32 v111, v62, v63
	s_waitcnt lgkmcnt(0)
	v_add_f32_e32 v210, v210, v197
	ds_bpermute_b32 v197, v192, v210
	v_cvt_pk_bf16_f32 v112, v64, v65
	v_cvt_pk_bf16_f32 v113, v66, v67
	v_cvt_pk_bf16_f32 v114, v68, v69
	v_cvt_pk_bf16_f32 v115, v70, v71
	v_cvt_pk_bf16_f32 v116, v72, v73
	v_cvt_pk_bf16_f32 v117, v74, v75
	v_cvt_pk_bf16_f32 v118, v76, v77
	v_cvt_pk_bf16_f32 v119, v78, v79
	v_cvt_pk_bf16_f32 v120, v80, v81
	v_cvt_pk_bf16_f32 v121, v82, v83
	v_cvt_pk_bf16_f32 v122, v84, v85
	v_cvt_pk_bf16_f32 v123, v86, v87
	v_cvt_pk_bf16_f32 v124, v88, v89
	v_cvt_pk_bf16_f32 v125, v90, v91
	v_cvt_pk_bf16_f32 v126, v92, v93
	v_cvt_pk_bf16_f32 v127, v94, v95
	s_waitcnt lgkmcnt(0)
	v_add_f32_e32 v210, v210, v197
	v_rcp_f32_e32 v208, v210
	s_waitcnt vmcnt(8)
	ds_read_b64_tr_b16 v[160:161], v182 offset:0
	ds_read_b64_tr_b16 v[162:163], v182 offset:2048
	ds_read_b64_tr_b16 v[164:165], v183 offset:0
	ds_read_b64_tr_b16 v[166:167], v183 offset:2048
	ds_read_b64_tr_b16 v[168:169], v184 offset:0
	ds_read_b64_tr_b16 v[170:171], v184 offset:2048
	ds_read_b64_tr_b16 v[172:173], v185 offset:0
	ds_read_b64_tr_b16 v[174:175], v185 offset:2048
	s_mov_b32 m0, s49
	s_nop 0
	global_load_lds_dwordx4 v12, s[22:23]
	global_load_lds_dwordx4 v13, s[22:23] offset:1024
	global_load_lds_dwordx4 v14, s[22:23] offset:2048
	global_load_lds_dwordx4 v15, s[22:23] offset:3072
	s_waitcnt lgkmcnt(0)
	v_mfma_f32_16x16x32_bf16 v[128:131], v[160:163], v[96:99], 0
	v_mfma_f32_16x16x32_bf16 v[132:135], v[164:167], v[96:99], 0
	v_mfma_f32_16x16x32_bf16 v[136:139], v[168:171], v[96:99], 0
	v_mfma_f32_16x16x32_bf16 v[140:143], v[172:175], v[96:99], 0
	s_waitcnt vmcnt(8)
	ds_read_b64_tr_b16 v[160:161], v182 offset:4096
	ds_read_b64_tr_b16 v[162:163], v182 offset:6144
	ds_read_b64_tr_b16 v[164:165], v183 offset:4096
	ds_read_b64_tr_b16 v[166:167], v183 offset:6144
	ds_read_b64_tr_b16 v[168:169], v184 offset:4096
	ds_read_b64_tr_b16 v[170:171], v184 offset:6144
	ds_read_b64_tr_b16 v[172:173], v185 offset:4096
	ds_read_b64_tr_b16 v[174:175], v185 offset:6144
	s_mov_b32 m0, s46
	s_nop 0
	global_load_lds_dwordx4 v16, s[22:23]
	global_load_lds_dwordx4 v18, s[22:23] offset:1024
	global_load_lds_dwordx4 v19, s[22:23] offset:2048
	global_load_lds_dwordx4 v20, s[22:23] offset:3072
	s_waitcnt lgkmcnt(0)
	v_mfma_f32_16x16x32_bf16 v[128:131], v[160:163], v[100:103], v[128:131]
	v_mfma_f32_16x16x32_bf16 v[132:135], v[164:167], v[100:103], v[132:135]
	v_mfma_f32_16x16x32_bf16 v[136:139], v[168:171], v[100:103], v[136:139]
	v_mfma_f32_16x16x32_bf16 v[140:143], v[172:175], v[100:103], v[140:143]
	s_waitcnt vmcnt(8)
	ds_read_b64_tr_b16 v[160:161], v182 offset:8192
	ds_read_b64_tr_b16 v[162:163], v182 offset:10240
	ds_read_b64_tr_b16 v[164:165], v183 offset:8192
	ds_read_b64_tr_b16 v[166:167], v183 offset:10240
	ds_read_b64_tr_b16 v[168:169], v184 offset:8192
	ds_read_b64_tr_b16 v[170:171], v184 offset:10240
	ds_read_b64_tr_b16 v[172:173], v185 offset:8192
	ds_read_b64_tr_b16 v[174:175], v185 offset:10240
	s_mov_b32 m0, s47
	s_nop 0
	global_load_lds_dwordx4 v21, s[22:23]
	global_load_lds_dwordx4 v22, s[22:23] offset:1024
	global_load_lds_dwordx4 v23, s[22:23] offset:2048
	global_load_lds_dwordx4 v24, s[22:23] offset:3072
	s_waitcnt lgkmcnt(0)
	v_mfma_f32_16x16x32_bf16 v[128:131], v[160:163], v[104:107], v[128:131]
	v_mfma_f32_16x16x32_bf16 v[132:135], v[164:167], v[104:107], v[132:135]
	v_mfma_f32_16x16x32_bf16 v[136:139], v[168:171], v[104:107], v[136:139]
	v_mfma_f32_16x16x32_bf16 v[140:143], v[172:175], v[104:107], v[140:143]
	s_waitcnt vmcnt(8)
	ds_read_b64_tr_b16 v[160:161], v182 offset:12288
	ds_read_b64_tr_b16 v[162:163], v182 offset:14336
	ds_read_b64_tr_b16 v[164:165], v183 offset:12288
	ds_read_b64_tr_b16 v[166:167], v183 offset:14336
	ds_read_b64_tr_b16 v[168:169], v184 offset:12288
	ds_read_b64_tr_b16 v[170:171], v184 offset:14336
	ds_read_b64_tr_b16 v[172:173], v185 offset:12288
	ds_read_b64_tr_b16 v[174:175], v185 offset:14336
	s_mov_b32 m0, s48
	s_nop 0
	global_load_lds_dwordx4 v25, s[22:23]
	global_load_lds_dwordx4 v26, s[22:23] offset:1024
	global_load_lds_dwordx4 v27, s[22:23] offset:2048
	global_load_lds_dwordx4 v28, s[22:23] offset:3072
	s_waitcnt lgkmcnt(0)
; __device__ __forceinline__ void phase_attn(KP kp, int l, unsigned char* shm) {
;     ...
;           oacc[0] = __builtin_amdgcn_mfma_f32_16x16x32_bf16(a0, pf[s8], oacc[0], 0, 0, 0);
;           oacc[1] = __builtin_amdgcn_mfma_f32_16x16x32_bf16(a1, pf[s8], oacc[1], 0, 0, 0);
;           oacc[2] = __builtin_amdgcn_mfma_f32_16x16x32_bf16(a2, pf[s8], oacc[2], 0, 0, 0);
;           oacc[3] = __builtin_amdgcn_mfma_f32_16x16x32_bf16(a3, pf[s8], oacc[3], 0, 0, 0);
;           if (kvh == 0 && s8 == 3) {
; #pragma unroll
;             for (int k8 = 0; k8 < 8; ++k8) {
;               const int idx = selw[k8 * 16 + nn];
;               const bf16_t* kp = kbase + (size_t)idx * 128 + 64 + kg * 8;
;               kpre[k8][0] = *(const bf16x8*)kp;
;               kpre[k8][1] = *(const bf16x8*)(kp + 32);
;             }
;           }
;         }
;         __builtin_amdgcn_sched_barrier(0);
;       }
;       if (nn < 4) {
; #pragma unroll
;         for (int c = 0; c < 4; ++c) {
;           u32x2 ow;
;           ow[0] = cvt_pk_bf16(oacc[c][0] * inv, oacc[c][1] * inv);
;           ow[1] = cvt_pk_bf16(oacc[c][2] * inv, oacc[c][3] * inv);
;           *(u32x2*)((bf16_t*)(ws + W_OA) + (size_t)r * 512 + (kvh * 4 + nn) * 64 + 16 * c + 4 * kg) = ow;
;         }
;       }
	v_mfma_f32_16x16x32_bf16 v[128:131], v[160:163], v[108:111], v[128:131]
	v_mfma_f32_16x16x32_bf16 v[132:135], v[164:167], v[108:111], v[132:135]
	v_mfma_f32_16x16x32_bf16 v[136:139], v[168:171], v[108:111], v[136:139]
	v_mfma_f32_16x16x32_bf16 v[140:143], v[172:175], v[108:111], v[140:143]
	s_waitcnt vmcnt(8)
	ds_read_b64_tr_b16 v[160:161], v182 offset:0
	ds_read_b64_tr_b16 v[162:163], v182 offset:2048
	ds_read_b64_tr_b16 v[164:165], v183 offset:0
	ds_read_b64_tr_b16 v[166:167], v183 offset:2048
	ds_read_b64_tr_b16 v[168:169], v184 offset:0
	ds_read_b64_tr_b16 v[170:171], v184 offset:2048
	ds_read_b64_tr_b16 v[172:173], v185 offset:0
	ds_read_b64_tr_b16 v[174:175], v185 offset:2048
	s_mov_b32 m0, s49
	s_nop 0
	global_load_lds_dwordx4 v29, s[22:23]
	global_load_lds_dwordx4 v30, s[22:23] offset:1024
	global_load_lds_dwordx4 v31, s[22:23] offset:2048
	global_load_lds_dwordx4 v219, s[22:23] offset:3072
	s_waitcnt lgkmcnt(0)
	v_mfma_f32_16x16x32_bf16 v[128:131], v[160:163], v[112:115], v[128:131]
	v_mfma_f32_16x16x32_bf16 v[132:135], v[164:167], v[112:115], v[132:135]
	v_mfma_f32_16x16x32_bf16 v[136:139], v[168:171], v[112:115], v[136:139]
	v_mfma_f32_16x16x32_bf16 v[140:143], v[172:175], v[112:115], v[140:143]
	s_waitcnt vmcnt(8)
	ds_read_b64_tr_b16 v[160:161], v182 offset:4096
	ds_read_b64_tr_b16 v[162:163], v182 offset:6144
	ds_read_b64_tr_b16 v[164:165], v183 offset:4096
	ds_read_b64_tr_b16 v[166:167], v183 offset:6144
	ds_read_b64_tr_b16 v[168:169], v184 offset:4096
	ds_read_b64_tr_b16 v[170:171], v184 offset:6144
	ds_read_b64_tr_b16 v[172:173], v185 offset:4096
	ds_read_b64_tr_b16 v[174:175], v185 offset:6144
	s_mov_b32 m0, s46
	s_nop 0
	global_load_lds_dwordx4 v0, s[24:25]
	global_load_lds_dwordx4 v1, s[24:25] offset:1024
	global_load_lds_dwordx4 v2, s[24:25] offset:2048
	global_load_lds_dwordx4 v3, s[24:25] offset:3072
	s_waitcnt lgkmcnt(0)
	v_mfma_f32_16x16x32_bf16 v[128:131], v[160:163], v[116:119], v[128:131]
	v_mfma_f32_16x16x32_bf16 v[132:135], v[164:167], v[116:119], v[132:135]
	v_mfma_f32_16x16x32_bf16 v[136:139], v[168:171], v[116:119], v[136:139]
	v_mfma_f32_16x16x32_bf16 v[140:143], v[172:175], v[116:119], v[140:143]
	s_waitcnt vmcnt(8)
	ds_read_b64_tr_b16 v[160:161], v182 offset:8192
	ds_read_b64_tr_b16 v[162:163], v182 offset:10240
	ds_read_b64_tr_b16 v[164:165], v183 offset:8192
	ds_read_b64_tr_b16 v[166:167], v183 offset:10240
	ds_read_b64_tr_b16 v[168:169], v184 offset:8192
	ds_read_b64_tr_b16 v[170:171], v184 offset:10240
	ds_read_b64_tr_b16 v[172:173], v185 offset:8192
	ds_read_b64_tr_b16 v[174:175], v185 offset:10240
	s_mov_b32 m0, s47
	s_nop 0
	global_load_lds_dwordx4 v4, s[24:25]
	global_load_lds_dwordx4 v5, s[24:25] offset:1024
	global_load_lds_dwordx4 v6, s[24:25] offset:2048
	global_load_lds_dwordx4 v7, s[24:25] offset:3072
	s_waitcnt lgkmcnt(0)
	v_mfma_f32_16x16x32_bf16 v[128:131], v[160:163], v[120:123], v[128:131]
	v_mfma_f32_16x16x32_bf16 v[132:135], v[164:167], v[120:123], v[132:135]
	v_mfma_f32_16x16x32_bf16 v[136:139], v[168:171], v[120:123], v[136:139]
	v_mfma_f32_16x16x32_bf16 v[140:143], v[172:175], v[120:123], v[140:143]
	s_waitcnt vmcnt(8)
	ds_read_b64_tr_b16 v[160:161], v182 offset:12288
	ds_read_b64_tr_b16 v[162:163], v182 offset:14336
	ds_read_b64_tr_b16 v[164:165], v183 offset:12288
	ds_read_b64_tr_b16 v[166:167], v183 offset:14336
	ds_read_b64_tr_b16 v[168:169], v184 offset:12288
	ds_read_b64_tr_b16 v[170:171], v184 offset:14336
	ds_read_b64_tr_b16 v[172:173], v185 offset:12288
	ds_read_b64_tr_b16 v[174:175], v185 offset:14336
	s_mov_b32 m0, s48
	s_nop 0
	global_load_lds_dwordx4 v8, s[24:25]
	global_load_lds_dwordx4 v9, s[24:25] offset:1024
	global_load_lds_dwordx4 v10, s[24:25] offset:2048
	global_load_lds_dwordx4 v11, s[24:25] offset:3072
	s_waitcnt lgkmcnt(0)
	v_mfma_f32_16x16x32_bf16 v[128:131], v[160:163], v[124:127], v[128:131]
	v_mfma_f32_16x16x32_bf16 v[132:135], v[164:167], v[124:127], v[132:135]
	v_mfma_f32_16x16x32_bf16 v[136:139], v[168:171], v[124:127], v[136:139]
	v_mfma_f32_16x16x32_bf16 v[140:143], v[172:175], v[124:127], v[140:143]
	s_nop 7
	s_nop 3
	v_mul_f32_e32 v128, v208, v128
	v_mul_f32_e32 v129, v208, v129
	v_mul_f32_e32 v130, v208, v130
	v_mul_f32_e32 v131, v208, v131
	v_cvt_pk_bf16_f32 v200, v128, v129
	v_cvt_pk_bf16_f32 v201, v130, v131
	v_mul_f32_e32 v132, v208, v132
	v_mul_f32_e32 v133, v208, v133
	v_mul_f32_e32 v134, v208, v134
	v_mul_f32_e32 v135, v208, v135
	v_cvt_pk_bf16_f32 v202, v132, v133
	v_cvt_pk_bf16_f32 v203, v134, v135
	v_mul_f32_e32 v136, v208, v136
	v_mul_f32_e32 v137, v208, v137
	v_mul_f32_e32 v138, v208, v138
	v_mul_f32_e32 v139, v208, v139
	v_cvt_pk_bf16_f32 v204, v136, v137
	v_cvt_pk_bf16_f32 v205, v138, v139
	v_mul_f32_e32 v140, v208, v140
	v_mul_f32_e32 v141, v208, v141
	v_mul_f32_e32 v142, v208, v142
	v_mul_f32_e32 v143, v208, v143
	v_cvt_pk_bf16_f32 v206, v140, v141
	v_cvt_pk_bf16_f32 v207, v142, v143
	s_mov_b64 exec, s[42:43]
	global_store_dwordx2 v190, v[200:201], s[34:35] offset:0 sc1
	global_store_dwordx2 v190, v[202:203], s[34:35] offset:32 sc1
	global_store_dwordx2 v190, v[204:205], s[34:35] offset:64 sc1
	global_store_dwordx2 v190, v[206:207], s[34:35] offset:96 sc1
	s_mov_b64 exec, -1
	s_waitcnt vmcnt(12)
	ds_read_b128 v[160:163], v180 offset:0
	ds_read_b128 v[164:167], v181 offset:0
	ds_read_b128 v[168:171], v180 offset:2048
	ds_read_b128 v[172:175], v181 offset:2048
	s_add_i32 s50, s2, s4
	s_cmp_lg_u32 s5, 0
	s_cbranch_scc1 .Lattn_nq_7
	s_cmp_lt_i32 s50, 0x8000
	s_cbranch_scc1 .Lattn_nq_7
	s_lshl_b32 s6, s57, 1
	s_add_i32 s6, s6, s56
	s_add_i32 s6, s6, 0x8000
	s_cmp_lt_u32 s56, 2
	s_cselect_b32 s6, s6, 0x10000
	s_cmp_ge_i32 s2, 0x8000
	s_cselect_b32 s50, 0x10000, s6

; __device__ __forceinline__ void phase_attn(KP kp, int l, unsigned char* shm) {
;     ...
;       float mx = -1e30f;
; #pragma unroll
;       for (int kb = 0; kb < 16; ++kb)
; #pragma unroll
;         for (int j = 0; j < 4; ++j) {
;           const int key = kb * 16 + kg * 4 + j;
;           lg[kb][j] = key < cnt ? lg[kb][j] : -1e30f;
;           mx = fmaxf(mx, lg[kb][j]);
;         }
;       mx = fmaxf(mx, __shfl_xor(mx, 16));
;       mx = fmaxf(mx, __shfl_xor(mx, 32));
;       float sum = 0.f;
; #pragma unroll
;       for (int kb = 0; kb < 16; ++kb)
; #pragma unroll
;         for (int j = 0; j < 4; ++j) { lg[kb][j] = __builtin_amdgcn_exp2f(lg[kb][j] - mx); sum += lg[kb][j]; }
;       sum += __shfl_xor(sum, 16);
;       sum += __shfl_xor(sum, 32);
;       const float inv = 1.f / sum;
.Lattn_nomask_11:
	v_max3_f32 v176, v32, v33, v34
	v_max3_f32 v176, v176, v35, v36
	v_max3_f32 v176, v176, v37, v38
	v_max3_f32 v176, v176, v39, v40
	v_max3_f32 v176, v176, v41, v42
	v_max3_f32 v176, v176, v43, v44
	v_max3_f32 v176, v176, v45, v46
	v_max3_f32 v176, v176, v47, v48
	v_max3_f32 v176, v176, v49, v50
	v_max3_f32 v176, v176, v51, v52
	v_max3_f32 v176, v176, v53, v54
	v_max3_f32 v176, v176, v55, v56
	v_max3_f32 v176, v176, v57, v58
	v_max3_f32 v176, v176, v59, v60
	v_max3_f32 v176, v176, v61, v62
	v_max3_f32 v176, v176, v63, v64
	v_max3_f32 v176, v176, v65, v66
	v_max3_f32 v176, v176, v67, v68
	v_max3_f32 v176, v176, v69, v70
	v_max3_f32 v176, v176, v71, v72
	v_max3_f32 v176, v176, v73, v74
	v_max3_f32 v176, v176, v75, v76
	v_max3_f32 v176, v176, v77, v78
	v_max3_f32 v176, v176, v79, v80
	v_max3_f32 v176, v176, v81, v82
	v_max3_f32 v176, v176, v83, v84
	v_max3_f32 v176, v176, v85, v86
	v_max3_f32 v176, v176, v87, v88
	v_max3_f32 v176, v176, v89, v90
	v_max3_f32 v176, v176, v91, v92
	v_max3_f32 v176, v176, v93, v94
	v_max_f32_e32 v176, v176, v95
	ds_bpermute_b32 v197, v191, v176
	s_waitcnt lgkmcnt(0)
	v_max_f32_e32 v176, v176, v197
	ds_bpermute_b32 v197, v192, v176
	s_waitcnt lgkmcnt(0)
	v_max_f32_e32 v176, v176, v197
	v_mov_b32_e32 v177, v176
	v_pk_add_f32 v[32:33], v[32:33], v[176:177] neg_lo:[0,1] neg_hi:[0,1]
	v_pk_add_f32 v[34:35], v[34:35], v[176:177] neg_lo:[0,1] neg_hi:[0,1]
	v_pk_add_f32 v[36:37], v[36:37], v[176:177] neg_lo:[0,1] neg_hi:[0,1]
	v_pk_add_f32 v[38:39], v[38:39], v[176:177] neg_lo:[0,1] neg_hi:[0,1]
	v_pk_add_f32 v[40:41], v[40:41], v[176:177] neg_lo:[0,1] neg_hi:[0,1]
	v_pk_add_f32 v[42:43], v[42:43], v[176:177] neg_lo:[0,1] neg_hi:[0,1]
	v_pk_add_f32 v[44:45], v[44:45], v[176:177] neg_lo:[0,1] neg_hi:[0,1]
	v_pk_add_f32 v[46:47], v[46:47], v[176:177] neg_lo:[0,1] neg_hi:[0,1]
	v_pk_add_f32 v[48:49], v[48:49], v[176:177] neg_lo:[0,1] neg_hi:[0,1]
	v_pk_add_f32 v[50:51], v[50:51], v[176:177] neg_lo:[0,1] neg_hi:[0,1]
	v_pk_add_f32 v[52:53], v[52:53], v[176:177] neg_lo:[0,1] neg_hi:[0,1]
	v_pk_add_f32 v[54:55], v[54:55], v[176:177] neg_lo:[0,1] neg_hi:[0,1]
	v_pk_add_f32 v[56:57], v[56:57], v[176:177] neg_lo:[0,1] neg_hi:[0,1]
	v_pk_add_f32 v[58:59], v[58:59], v[176:177] neg_lo:[0,1] neg_hi:[0,1]
	v_pk_add_f32 v[60:61], v[60:61], v[176:177] neg_lo:[0,1] neg_hi:[0,1]
	v_pk_add_f32 v[62:63], v[62:63], v[176:177] neg_lo:[0,1] neg_hi:[0,1]
	v_pk_add_f32 v[64:65], v[64:65], v[176:177] neg_lo:[0,1] neg_hi:[0,1]
	v_pk_add_f32 v[66:67], v[66:67], v[176:177] neg_lo:[0,1] neg_hi:[0,1]
	v_pk_add_f32 v[68:69], v[68:69], v[176:177] neg_lo:[0,1] neg_hi:[0,1]
	v_pk_add_f32 v[70:71], v[70:71], v[176:177] neg_lo:[0,1] neg_hi:[0,1]
	v_pk_add_f32 v[72:73], v[72:73], v[176:177] neg_lo:[0,1] neg_hi:[0,1]
	v_pk_add_f32 v[74:75], v[74:75], v[176:177] neg_lo:[0,1] neg_hi:[0,1]
	v_pk_add_f32 v[76:77], v[76:77], v[176:177] neg_lo:[0,1] neg_hi:[0,1]
	v_pk_add_f32 v[78:79], v[78:79], v[176:177] neg_lo:[0,1] neg_hi:[0,1]
	v_pk_add_f32 v[80:81], v[80:81], v[176:177] neg_lo:[0,1] neg_hi:[0,1]
	v_pk_add_f32 v[82:83], v[82:83], v[176:177] neg_lo:[0,1] neg_hi:[0,1]
	v_pk_add_f32 v[84:85], v[84:85], v[176:177] neg_lo:[0,1] neg_hi:[0,1]
	v_pk_add_f32 v[86:87], v[86:87], v[176:177] neg_lo:[0,1] neg_hi:[0,1]
	v_pk_add_f32 v[88:89], v[88:89], v[176:177] neg_lo:[0,1] neg_hi:[0,1]
	v_pk_add_f32 v[90:91], v[90:91], v[176:177] neg_lo:[0,1] neg_hi:[0,1]
	v_pk_add_f32 v[92:93], v[92:93], v[176:177] neg_lo:[0,1] neg_hi:[0,1]
	v_pk_add_f32 v[94:95], v[94:95], v[176:177] neg_lo:[0,1] neg_hi:[0,1]
	v_exp_f32_e32 v32, v32
	v_exp_f32_e32 v33, v33
	v_exp_f32_e32 v34, v34
	v_exp_f32_e32 v35, v35
	v_exp_f32_e32 v36, v36
	v_exp_f32_e32 v37, v37
	v_pk_add_f32 v[178:179], v[32:33], v[34:35]
	v_exp_f32_e32 v38, v38
	v_exp_f32_e32 v39, v39
	v_pk_add_f32 v[178:179], v[178:179], v[36:37]
	v_exp_f32_e32 v40, v40
	v_exp_f32_e32 v41, v41
	v_pk_add_f32 v[178:179], v[178:179], v[38:39]
	v_exp_f32_e32 v42, v42
	v_exp_f32_e32 v43, v43
	v_pk_add_f32 v[178:179], v[178:179], v[40:41]
	v_exp_f32_e32 v44, v44
	v_exp_f32_e32 v45, v45
	v_pk_add_f32 v[178:179], v[178:179], v[42:43]
	v_exp_f32_e32 v46, v46
	v_exp_f32_e32 v47, v47
	v_pk_add_f32 v[178:179], v[178:179], v[44:45]
	v_exp_f32_e32 v48, v48
	v_exp_f32_e32 v49, v49
	v_pk_add_f32 v[178:179], v[178:179], v[46:47]
	v_exp_f32_e32 v50, v50
	v_exp_f32_e32 v51, v51
	v_pk_add_f32 v[178:179], v[178:179], v[48:49]
	v_exp_f32_e32 v52, v52
	v_exp_f32_e32 v53, v53
	v_pk_add_f32 v[178:179], v[178:179], v[50:51]
	v_exp_f32_e32 v54, v54
	v_exp_f32_e32 v55, v55
	v_pk_add_f32 v[178:179], v[178:179], v[52:53]
	v_exp_f32_e32 v56, v56
	v_exp_f32_e32 v57, v57
	v_pk_add_f32 v[178:179], v[178:179], v[54:55]
	v_exp_f32_e32 v58, v58
	v_exp_f32_e32 v59, v59
	v_pk_add_f32 v[178:179], v[178:179], v[56:57]
	v_exp_f32_e32 v60, v60
	v_exp_f32_e32 v61, v61
	v_pk_add_f32 v[178:179], v[178:179], v[58:59]
	v_exp_f32_e32 v62, v62
	v_exp_f32_e32 v63, v63
	v_pk_add_f32 v[178:179], v[178:179], v[60:61]
	v_exp_f32_e32 v64, v64
	v_exp_f32_e32 v65, v65
	v_pk_add_f32 v[178:179], v[178:179], v[62:63]
	v_exp_f32_e32 v66, v66
	v_exp_f32_e32 v67, v67
	v_pk_add_f32 v[178:179], v[178:179], v[64:65]
	v_exp_f32_e32 v68, v68
	v_exp_f32_e32 v69, v69
	v_pk_add_f32 v[178:179], v[178:179], v[66:67]
	v_exp_f32_e32 v70, v70
	v_exp_f32_e32 v71, v71
	v_pk_add_f32 v[178:179], v[178:179], v[68:69]
	v_exp_f32_e32 v72, v72
	v_exp_f32_e32 v73, v73
	v_pk_add_f32 v[178:179], v[178:179], v[70:71]
	v_exp_f32_e32 v74, v74
	v_exp_f32_e32 v75, v75
	v_pk_add_f32 v[178:179], v[178:179], v[72:73]
	v_exp_f32_e32 v76, v76
	v_exp_f32_e32 v77, v77
	v_pk_add_f32 v[178:179], v[178:179], v[74:75]
; __device__ __forceinline__ void phase_attn(KP kp, int l, unsigned char* shm) {
;     ...
;       float sum = 0.f;
; #pragma unroll
;       for (int kb = 0; kb < 16; ++kb)
; #pragma unroll
;         for (int j = 0; j < 4; ++j) { lg[kb][j] = __builtin_amdgcn_exp2f(lg[kb][j] - mx); sum += lg[kb][j]; }
;       sum += __shfl_xor(sum, 16);
;       sum += __shfl_xor(sum, 32);
;       const float inv = 1.f / sum;
;       bf16x8 pf[8];
; #pragma unroll
;       for (int s8 = 0; s8 < 8; ++s8) {
;         u32x4 pk;
;         pk[0] = cvt_pk_bf16(lg[2 * s8][0], lg[2 * s8][1]);
;         pk[1] = cvt_pk_bf16(lg[2 * s8][2], lg[2 * s8][3]);
;         pk[2] = cvt_pk_bf16(lg[2 * s8 + 1][0], lg[2 * s8 + 1][1]);
;         pk[3] = cvt_pk_bf16(lg[2 * s8 + 1][2], lg[2 * s8 + 1][3]);
;         pf[s8] = __builtin_bit_cast(bf16x8, pk);
;       }
;       f32x4 oacc[4];
; #pragma unroll
;       for (int c = 0; c < 4; ++c) oacc[c] = (f32x4){0.f, 0.f, 0.f, 0.f};
;       for (int repV = 0; repV < ((PROBE & 256) ? 2 : 1); ++repV)
;       {
;         if (repV) {
; #pragma unroll
;           for (int c = 0; c < 4; ++c) oacc[c] = (f32x4){0.f, 0.f, 0.f, 0.f};
;         }
; #pragma unroll
;         for (int i = 16; i < 32; ++i) {
;           const int idx = selw[i * 8 + ks8];
;           vr[i] = *(const u32x4*)(vbase + (size_t)idx * 128 + kvh * 64 + dc * 8);
;         }
; #pragma unroll
;         for (int s8 = 0; s8 < 8; ++s8) {
; #pragma unroll
;           for (int it = 0; it < 4; ++it) *(u32x4*)(tileb + (it * 8 + ks8) * 144 + dc * 16) = vr[s8 * 4 + it];
;           u32x2 t0, t1, t2, t3, t4, t5, t6, t7;
;           asm volatile(
;               "ds_read_b64_tr_b16 %0, %8\n\tds_read_b64_tr_b16 %1, %8 offset:2304\n\t"
;               "ds_read_b64_tr_b16 %2, %8 offset:32\n\tds_read_b64_tr_b16 %3, %8 offset:2336\n\t"
;               "ds_read_b64_tr_b16 %4, %8 offset:64\n\tds_read_b64_tr_b16 %5, %8 offset:2368\n\t"
;               "ds_read_b64_tr_b16 %6, %8 offset:96\n\tds_read_b64_tr_b16 %7, %8 offset:2400\n\t"
;               "s_waitcnt lgkmcnt(0)"
;               : "=&v"(t0), "=&v"(t1), "=&v"(t2), "=&v"(t3), "=&v"(t4), "=&v"(t5), "=&v"(t6), "=&v"(t7)
;               : "v"(tr_addr)
;               : "memory");
;           const bf16x8 a0 = __builtin_bit_cast(bf16x8, (u32x4){t0[0], t0[1], t1[0], t1[1]});
;           const bf16x8 a1 = __builtin_bit_cast(bf16x8, (u32x4){t2[0], t2[1], t3[0], t3[1]});
	v_exp_f32_e32 v78, v78
	v_exp_f32_e32 v79, v79
	v_pk_add_f32 v[178:179], v[178:179], v[76:77]
	v_exp_f32_e32 v80, v80
	v_exp_f32_e32 v81, v81
	v_pk_add_f32 v[178:179], v[178:179], v[78:79]
	v_exp_f32_e32 v82, v82
	v_exp_f32_e32 v83, v83
	v_pk_add_f32 v[178:179], v[178:179], v[80:81]
	v_exp_f32_e32 v84, v84
	v_exp_f32_e32 v85, v85
	v_pk_add_f32 v[178:179], v[178:179], v[82:83]
	v_exp_f32_e32 v86, v86
	v_exp_f32_e32 v87, v87
	v_pk_add_f32 v[178:179], v[178:179], v[84:85]
	v_exp_f32_e32 v88, v88
	v_exp_f32_e32 v89, v89
	v_pk_add_f32 v[178:179], v[178:179], v[86:87]
	v_exp_f32_e32 v90, v90
	v_exp_f32_e32 v91, v91
	v_pk_add_f32 v[178:179], v[178:179], v[88:89]
	v_exp_f32_e32 v92, v92
	v_exp_f32_e32 v93, v93
	v_pk_add_f32 v[178:179], v[178:179], v[90:91]
	v_exp_f32_e32 v94, v94
	v_exp_f32_e32 v95, v95
	v_pk_add_f32 v[178:179], v[178:179], v[92:93]
	s_nop 0
	v_pk_add_f32 v[178:179], v[178:179], v[94:95]
	v_add_f32_e32 v210, v178, v179
	ds_bpermute_b32 v197, v191, v210
	v_cvt_pk_bf16_f32 v96, v32, v33
	v_cvt_pk_bf16_f32 v97, v34, v35
	v_cvt_pk_bf16_f32 v98, v36, v37
	v_cvt_pk_bf16_f32 v99, v38, v39
	v_cvt_pk_bf16_f32 v100, v40, v41
	v_cvt_pk_bf16_f32 v101, v42, v43
	v_cvt_pk_bf16_f32 v102, v44, v45
	v_cvt_pk_bf16_f32 v103, v46, v47
	v_cvt_pk_bf16_f32 v104, v48, v49
	v_cvt_pk_bf16_f32 v105, v50, v51
	v_cvt_pk_bf16_f32 v106, v52, v53
	v_cvt_pk_bf16_f32 v107, v54, v55
	v_cvt_pk_bf16_f32 v108, v56, v57
	v_cvt_pk_bf16_f32 v109, v58, v59
	v_cvt_pk_bf16_f32 v110, v60, v61
	v_cvt_pk_bf16_f32 v111, v62, v63
	s_waitcnt lgkmcnt(0)
	v_add_f32_e32 v210, v210, v197
	ds_bpermute_b32 v197, v192, v210
	v_cvt_pk_bf16_f32 v112, v64, v65
	v_cvt_pk_bf16_f32 v113, v66, v67
	v_cvt_pk_bf16_f32 v114, v68, v69
	v_cvt_pk_bf16_f32 v115, v70, v71
	v_cvt_pk_bf16_f32 v116, v72, v73
	v_cvt_pk_bf16_f32 v117, v74, v75
	v_cvt_pk_bf16_f32 v118, v76, v77
	v_cvt_pk_bf16_f32 v119, v78, v79
	v_cvt_pk_bf16_f32 v120, v80, v81
	v_cvt_pk_bf16_f32 v121, v82, v83
	v_cvt_pk_bf16_f32 v122, v84, v85
	v_cvt_pk_bf16_f32 v123, v86, v87
	v_cvt_pk_bf16_f32 v124, v88, v89
	v_cvt_pk_bf16_f32 v125, v90, v91
	v_cvt_pk_bf16_f32 v126, v92, v93
	v_cvt_pk_bf16_f32 v127, v94, v95
	s_waitcnt lgkmcnt(0)
	v_add_f32_e32 v210, v210, v197
	v_rcp_f32_e32 v208, v210
	s_waitcnt vmcnt(8)
	ds_read_b64_tr_b16 v[160:161], v182 offset:0
	ds_read_b64_tr_b16 v[162:163], v182 offset:2048
	ds_read_b64_tr_b16 v[164:165], v183 offset:0
	ds_read_b64_tr_b16 v[166:167], v183 offset:2048
	ds_read_b64_tr_b16 v[168:169], v184 offset:0
	ds_read_b64_tr_b16 v[170:171], v184 offset:2048
	ds_read_b64_tr_b16 v[172:173], v185 offset:0
	ds_read_b64_tr_b16 v[174:175], v185 offset:2048
	s_mov_b64 exec, s[42:43]
	global_load_dwordx4 v[144:147], v189, s[40:41]
	global_load_dwordx4 v[148:151], v189, s[40:41] offset:64
	global_load_dwordx4 v[152:155], v189, s[40:41] offset:512
	global_load_dwordx4 v[156:159], v189, s[40:41] offset:576
	s_mov_b64 exec, -1
	s_mov_b32 m0, s49
	s_nop 0
	global_load_lds_dwordx4 v12, s[26:27]
	global_load_lds_dwordx4 v13, s[26:27] offset:1024
	global_load_lds_dwordx4 v14, s[26:27] offset:2048
	global_load_lds_dwordx4 v15, s[26:27] offset:3072
	s_waitcnt lgkmcnt(0)
	v_mfma_f32_16x16x32_bf16 v[128:131], v[160:163], v[96:99], 0
	v_mfma_f32_16x16x32_bf16 v[132:135], v[164:167], v[96:99], 0
	v_mfma_f32_16x16x32_bf16 v[136:139], v[168:171], v[96:99], 0
	v_mfma_f32_16x16x32_bf16 v[140:143], v[172:175], v[96:99], 0
	s_waitcnt vmcnt(12)
	ds_read_b64_tr_b16 v[160:161], v182 offset:4096
	ds_read_b64_tr_b16 v[162:163], v182 offset:6144
	ds_read_b64_tr_b16 v[164:165], v183 offset:4096
	ds_read_b64_tr_b16 v[166:167], v183 offset:6144
	ds_read_b64_tr_b16 v[168:169], v184 offset:4096
	ds_read_b64_tr_b16 v[170:171], v184 offset:6144
	ds_read_b64_tr_b16 v[172:173], v185 offset:4096
	ds_read_b64_tr_b16 v[174:175], v185 offset:6144
	s_mov_b32 m0, s46
	s_nop 0
	global_load_lds_dwordx4 v16, s[26:27]
	global_load_lds_dwordx4 v18, s[26:27] offset:1024
	global_load_lds_dwordx4 v19, s[26:27] offset:2048
	global_load_lds_dwordx4 v20, s[26:27] offset:3072
	s_waitcnt lgkmcnt(0)
	v_mfma_f32_16x16x32_bf16 v[128:131], v[160:163], v[100:103], v[128:131]
	v_mfma_f32_16x16x32_bf16 v[132:135], v[164:167], v[100:103], v[132:135]
	v_mfma_f32_16x16x32_bf16 v[136:139], v[168:171], v[100:103], v[136:139]
	v_mfma_f32_16x16x32_bf16 v[140:143], v[172:175], v[100:103], v[140:143]
	s_waitcnt vmcnt(12)
	ds_read_b64_tr_b16 v[160:161], v182 offset:8192
	ds_read_b64_tr_b16 v[162:163], v182 offset:10240
	ds_read_b64_tr_b16 v[164:165], v183 offset:8192
	ds_read_b64_tr_b16 v[166:167], v183 offset:10240
	ds_read_b64_tr_b16 v[168:169], v184 offset:8192
	ds_read_b64_tr_b16 v[170:171], v184 offset:10240
	ds_read_b64_tr_b16 v[172:173], v185 offset:8192
	ds_read_b64_tr_b16 v[174:175], v185 offset:10240
	s_mov_b32 m0, s47
	s_nop 0
	global_load_lds_dwordx4 v21, s[26:27]
	global_load_lds_dwordx4 v22, s[26:27] offset:1024
	global_load_lds_dwordx4 v23, s[26:27] offset:2048
	global_load_lds_dwordx4 v24, s[26:27] offset:3072
	s_waitcnt lgkmcnt(0)
	v_mfma_f32_16x16x32_bf16 v[128:131], v[160:163], v[104:107], v[128:131]
	v_mfma_f32_16x16x32_bf16 v[132:135], v[164:167], v[104:107], v[132:135]
	v_mfma_f32_16x16x32_bf16 v[136:139], v[168:171], v[104:107], v[136:139]
	v_mfma_f32_16x16x32_bf16 v[140:143], v[172:175], v[104:107], v[140:143]
	s_waitcnt vmcnt(8)
	ds_read_b64_tr_b16 v[160:161], v182 offset:12288
	ds_read_b64_tr_b16 v[162:163], v182 offset:14336
	ds_read_b64_tr_b16 v[164:165], v183 offset:12288
	ds_read_b64_tr_b16 v[166:167], v183 offset:14336
	ds_read_b64_tr_b16 v[168:169], v184 offset:12288
	ds_read_b64_tr_b16 v[170:171], v184 offset:14336
	ds_read_b64_tr_b16 v[172:173], v185 offset:12288
	ds_read_b64_tr_b16 v[174:175], v185 offset:14336
	s_mov_b32 m0, s48
	s_nop 0
	global_load_lds_dwordx4 v25, s[26:27]
	global_load_lds_dwordx4 v26, s[26:27] offset:1024
	global_load_lds_dwordx4 v27, s[26:27] offset:2048
	global_load_lds_dwordx4 v28, s[26:27] offset:3072
	s_waitcnt lgkmcnt(0)
; __device__ __forceinline__ void phase_attn(KP kp, int l, unsigned char* shm) {
;     ...
;       u32x2 sv = *(const u32x2*)(SEL + (size_t)r * 256 + lane * 4);
;       const int k0 = lane * 4;
;       unsigned a0 = sv[0] & 0xffffu, a1 = sv[0] >> 16, a2 = sv[1] & 0xffffu, a3 = sv[1] >> 16;
;       a0 = (k0 < cnt) ? a0 : 0u; a1 = (k0 + 1 < cnt) ? a1 : 0u; a2 = (k0 + 2 < cnt) ? a2 : 0u; a3 = (k0 + 3 < cnt) ? a3 : 0u;
;       u32x2 o;
;       o[0] = a0 | (a1 << 16); o[1] = a2 | (a3 << 16);
;       *(u32x2*)(selw + lane * 4) = o;
;     }
;     ...
;             for (int k8 = 0; k8 < 8; ++k8) {
;               const int idx = selw[(hb * 8 + k8) * 16 + nn];
;               const bf16_t* kp = kbase + (size_t)idx * 128 + kvh * 64 + kg * 8;
;               ka[k8][0] = *(const bf16x8*)kp;
;               ka[k8][1] = *(const bf16x8*)(kp + 32);
;             }
	v_mfma_f32_16x16x32_bf16 v[128:131], v[160:163], v[108:111], v[128:131]
	v_mfma_f32_16x16x32_bf16 v[132:135], v[164:167], v[108:111], v[132:135]
	v_mfma_f32_16x16x32_bf16 v[136:139], v[168:171], v[108:111], v[136:139]
	v_mfma_f32_16x16x32_bf16 v[140:143], v[172:175], v[108:111], v[140:143]
	s_waitcnt vmcnt(8)
	ds_read_b64_tr_b16 v[160:161], v182 offset:0
	ds_read_b64_tr_b16 v[162:163], v182 offset:2048
	ds_read_b64_tr_b16 v[164:165], v183 offset:0
	ds_read_b64_tr_b16 v[166:167], v183 offset:2048
	ds_read_b64_tr_b16 v[168:169], v184 offset:0
	ds_read_b64_tr_b16 v[170:171], v184 offset:2048
	ds_read_b64_tr_b16 v[172:173], v185 offset:0
	ds_read_b64_tr_b16 v[174:175], v185 offset:2048
	s_mov_b32 m0, s49
	s_nop 0
	global_load_lds_dwordx4 v29, s[26:27]
	global_load_lds_dwordx4 v30, s[26:27] offset:1024
	global_load_lds_dwordx4 v31, s[26:27] offset:2048
	global_load_lds_dwordx4 v219, s[26:27] offset:3072
	s_waitcnt lgkmcnt(0)
	v_mfma_f32_16x16x32_bf16 v[128:131], v[160:163], v[112:115], v[128:131]
	v_mfma_f32_16x16x32_bf16 v[132:135], v[164:167], v[112:115], v[132:135]
	v_mfma_f32_16x16x32_bf16 v[136:139], v[168:171], v[112:115], v[136:139]
	v_mfma_f32_16x16x32_bf16 v[140:143], v[172:175], v[112:115], v[140:143]
	s_lshr_b32 s6, s45, 2
	v_cmp_gt_u32_e32 vcc, s6, v252
	s_nop 1
	v_cndmask_b32_e32 v198, 0, v198, vcc
	v_cndmask_b32_e32 v199, 0, v199, vcc
	ds_write_b64 v186, v[198:199]
	ds_read_u16 v0, v187 offset:0
	ds_read_u16 v1, v187 offset:16
	ds_read_u16 v2, v187 offset:32
	ds_read_u16 v3, v187 offset:48
	ds_read_u16 v4, v187 offset:64
	ds_read_u16 v5, v187 offset:80
	ds_read_u16 v6, v187 offset:96
	ds_read_u16 v7, v187 offset:112
	s_waitcnt lgkmcnt(0)
	v_lshl_add_u32 v0, v0, 8, v193
	v_lshl_add_u32 v1, v1, 8, v194
	v_lshl_add_u32 v2, v2, 8, v195
	v_lshl_add_u32 v3, v3, 8, v196
	v_lshl_add_u32 v4, v4, 8, v193
	v_lshl_add_u32 v5, v5, 8, v194
	v_lshl_add_u32 v6, v6, 8, v195
	v_lshl_add_u32 v7, v7, 8, v196
	ds_read_u16 v8, v187 offset:128
	ds_read_u16 v9, v187 offset:144
	ds_read_u16 v10, v187 offset:160
	ds_read_u16 v11, v187 offset:176
	ds_read_u16 v12, v187 offset:192
	ds_read_u16 v13, v187 offset:208
	ds_read_u16 v14, v187 offset:224
	ds_read_u16 v15, v187 offset:240
	s_waitcnt lgkmcnt(0)
	v_lshl_add_u32 v8, v8, 8, v193
	v_lshl_add_u32 v9, v9, 8, v194
	v_lshl_add_u32 v10, v10, 8, v195
	v_lshl_add_u32 v11, v11, 8, v196
	v_lshl_add_u32 v12, v12, 8, v193
	v_lshl_add_u32 v13, v13, 8, v194
	v_lshl_add_u32 v14, v14, 8, v195
	v_lshl_add_u32 v15, v15, 8, v196
	ds_read_u16 v16, v187 offset:256
	ds_read_u16 v18, v187 offset:272
	ds_read_u16 v19, v187 offset:288
	ds_read_u16 v20, v187 offset:304
	ds_read_u16 v21, v187 offset:320
	ds_read_u16 v22, v187 offset:336
	ds_read_u16 v23, v187 offset:352
	ds_read_u16 v24, v187 offset:368
	s_waitcnt lgkmcnt(0)
	v_lshl_add_u32 v16, v16, 8, v193
	v_lshl_add_u32 v18, v18, 8, v194
	v_lshl_add_u32 v19, v19, 8, v195
	v_lshl_add_u32 v20, v20, 8, v196
	v_lshl_add_u32 v21, v21, 8, v193
	v_lshl_add_u32 v22, v22, 8, v194
	v_lshl_add_u32 v23, v23, 8, v195
	v_lshl_add_u32 v24, v24, 8, v196
	ds_read_u16 v25, v187 offset:384
	ds_read_u16 v26, v187 offset:400
	ds_read_u16 v27, v187 offset:416
	ds_read_u16 v28, v187 offset:432
	ds_read_u16 v29, v187 offset:448
	ds_read_u16 v30, v187 offset:464
	ds_read_u16 v31, v187 offset:480
	ds_read_u16 v219, v187 offset:496
	s_waitcnt lgkmcnt(0)
	v_lshl_add_u32 v25, v25, 8, v193
	v_lshl_add_u32 v26, v26, 8, v194
	v_lshl_add_u32 v27, v27, 8, v195
	v_lshl_add_u32 v28, v28, 8, v196
	v_lshl_add_u32 v29, v29, 8, v193
	v_lshl_add_u32 v30, v30, 8, v194
	v_lshl_add_u32 v31, v31, 8, v195
	v_lshl_add_u32 v219, v219, 8, v196
	s_waitcnt vmcnt(8)
; __device__ __forceinline__ void phase_attn(KP kp, int l, unsigned char* shm) {
;     ...
;         for (int s8 = 0; s8 < 8; ++s8) {
; #pragma unroll
;           for (int it = 0; it < 4; ++it) *(u32x4*)(tileb + (it * 8 + ks8) * 144 + dc * 16) = vr[s8 * 4 + it];
;           u32x2 t0, t1, t2, t3, t4, t5, t6, t7;
;           asm volatile(
;               "ds_read_b64_tr_b16 %0, %8\n\tds_read_b64_tr_b16 %1, %8 offset:2304\n\t"
;               "ds_read_b64_tr_b16 %2, %8 offset:32\n\tds_read_b64_tr_b16 %3, %8 offset:2336\n\t"
;               "ds_read_b64_tr_b16 %4, %8 offset:64\n\tds_read_b64_tr_b16 %5, %8 offset:2368\n\t"
;               "ds_read_b64_tr_b16 %6, %8 offset:96\n\tds_read_b64_tr_b16 %7, %8 offset:2400\n\t"
;               "s_waitcnt lgkmcnt(0)"
;               : "=&v"(t0), "=&v"(t1), "=&v"(t2), "=&v"(t3), "=&v"(t4), "=&v"(t5), "=&v"(t6), "=&v"(t7)
;               : "v"(tr_addr)
;               : "memory");
;           const bf16x8 a0 = __builtin_bit_cast(bf16x8, (u32x4){t0[0], t0[1], t1[0], t1[1]});
;           const bf16x8 a1 = __builtin_bit_cast(bf16x8, (u32x4){t2[0], t2[1], t3[0], t3[1]});
;           const bf16x8 a2 = __builtin_bit_cast(bf16x8, (u32x4){t4[0], t4[1], t5[0], t5[1]});
;           const bf16x8 a3 = __builtin_bit_cast(bf16x8, (u32x4){t6[0], t6[1], t7[0], t7[1]});
;           oacc[0] = __builtin_amdgcn_mfma_f32_16x16x32_bf16(a0, pf[s8], oacc[0], 0, 0, 0);
;           oacc[1] = __builtin_amdgcn_mfma_f32_16x16x32_bf16(a1, pf[s8], oacc[1], 0, 0, 0);
;           oacc[2] = __builtin_amdgcn_mfma_f32_16x16x32_bf16(a2, pf[s8], oacc[2], 0, 0, 0);
;           oacc[3] = __builtin_amdgcn_mfma_f32_16x16x32_bf16(a3, pf[s8], oacc[3], 0, 0, 0);
;           if (kvh == 0 && s8 == 3) {
; #pragma unroll
;             for (int k8 = 0; k8 < 8; ++k8) {
;               const int idx = selw[k8 * 16 + nn];
;               const bf16_t* kp = kbase + (size_t)idx * 128 + 64 + kg * 8;
;               kpre[k8][0] = *(const bf16x8*)kp;
;               kpre[k8][1] = *(const bf16x8*)(kp + 32);
;             }
;           }
;         }
;         __builtin_amdgcn_sched_barrier(0);
;       }
;       if (nn < 4) {
; #pragma unroll
;         for (int c = 0; c < 4; ++c) {
;           u32x2 ow;
;           ow[0] = cvt_pk_bf16(oacc[c][0] * inv, oacc[c][1] * inv);
;           ow[1] = cvt_pk_bf16(oacc[c][2] * inv, oacc[c][3] * inv);
	ds_read_b64_tr_b16 v[160:161], v182 offset:4096
	ds_read_b64_tr_b16 v[162:163], v182 offset:6144
	ds_read_b64_tr_b16 v[164:165], v183 offset:4096
	ds_read_b64_tr_b16 v[166:167], v183 offset:6144
	ds_read_b64_tr_b16 v[168:169], v184 offset:4096
	ds_read_b64_tr_b16 v[170:171], v184 offset:6144
	ds_read_b64_tr_b16 v[172:173], v185 offset:4096
	ds_read_b64_tr_b16 v[174:175], v185 offset:6144
	s_mov_b32 m0, s46
	s_nop 0
	global_load_lds_dwordx4 v0, s[28:29]
	global_load_lds_dwordx4 v1, s[28:29] offset:1024
	global_load_lds_dwordx4 v2, s[28:29] offset:2048
	global_load_lds_dwordx4 v3, s[28:29] offset:3072
	s_waitcnt lgkmcnt(0)
	v_mfma_f32_16x16x32_bf16 v[128:131], v[160:163], v[116:119], v[128:131]
	v_mfma_f32_16x16x32_bf16 v[132:135], v[164:167], v[116:119], v[132:135]
	v_mfma_f32_16x16x32_bf16 v[136:139], v[168:171], v[116:119], v[136:139]
	v_mfma_f32_16x16x32_bf16 v[140:143], v[172:175], v[116:119], v[140:143]
	s_waitcnt vmcnt(8)
	ds_read_b64_tr_b16 v[160:161], v182 offset:8192
	ds_read_b64_tr_b16 v[162:163], v182 offset:10240
	ds_read_b64_tr_b16 v[164:165], v183 offset:8192
	ds_read_b64_tr_b16 v[166:167], v183 offset:10240
	ds_read_b64_tr_b16 v[168:169], v184 offset:8192
	ds_read_b64_tr_b16 v[170:171], v184 offset:10240
	ds_read_b64_tr_b16 v[172:173], v185 offset:8192
	ds_read_b64_tr_b16 v[174:175], v185 offset:10240
	s_mov_b32 m0, s47
	s_nop 0
	global_load_lds_dwordx4 v4, s[28:29]
	global_load_lds_dwordx4 v5, s[28:29] offset:1024
	global_load_lds_dwordx4 v6, s[28:29] offset:2048
	global_load_lds_dwordx4 v7, s[28:29] offset:3072
	s_waitcnt lgkmcnt(0)
	v_mfma_f32_16x16x32_bf16 v[128:131], v[160:163], v[120:123], v[128:131]
	v_mfma_f32_16x16x32_bf16 v[132:135], v[164:167], v[120:123], v[132:135]
	v_mfma_f32_16x16x32_bf16 v[136:139], v[168:171], v[120:123], v[136:139]
	v_mfma_f32_16x16x32_bf16 v[140:143], v[172:175], v[120:123], v[140:143]
	s_waitcnt vmcnt(8)
	ds_read_b64_tr_b16 v[160:161], v182 offset:12288
	ds_read_b64_tr_b16 v[162:163], v182 offset:14336
	ds_read_b64_tr_b16 v[164:165], v183 offset:12288
	ds_read_b64_tr_b16 v[166:167], v183 offset:14336
	ds_read_b64_tr_b16 v[168:169], v184 offset:12288
	ds_read_b64_tr_b16 v[170:171], v184 offset:14336
	ds_read_b64_tr_b16 v[172:173], v185 offset:12288
	ds_read_b64_tr_b16 v[174:175], v185 offset:14336
	s_mov_b32 m0, s48
	s_nop 0
	global_load_lds_dwordx4 v8, s[28:29]
	global_load_lds_dwordx4 v9, s[28:29] offset:1024
	global_load_lds_dwordx4 v10, s[28:29] offset:2048
	global_load_lds_dwordx4 v11, s[28:29] offset:3072
	s_waitcnt lgkmcnt(0)
	v_mfma_f32_16x16x32_bf16 v[128:131], v[160:163], v[124:127], v[128:131]
	v_mfma_f32_16x16x32_bf16 v[132:135], v[164:167], v[124:127], v[132:135]
	v_mfma_f32_16x16x32_bf16 v[136:139], v[168:171], v[124:127], v[136:139]
	v_mfma_f32_16x16x32_bf16 v[140:143], v[172:175], v[124:127], v[140:143]
	s_nop 7
	s_nop 3
	v_mul_f32_e32 v128, v208, v128
	v_mul_f32_e32 v129, v208, v129
	v_mul_f32_e32 v130, v208, v130
	v_mul_f32_e32 v131, v208, v131
	v_cvt_pk_bf16_f32 v200, v128, v129
	v_cvt_pk_bf16_f32 v201, v130, v131
	v_mul_f32_e32 v132, v208, v132
	v_mul_f32_e32 v133, v208, v133
	v_mul_f32_e32 v134, v208, v134
	v_mul_f32_e32 v135, v208, v135
	v_cvt_pk_bf16_f32 v202, v132, v133
	v_cvt_pk_bf16_f32 v203, v134, v135
	v_mul_f32_e32 v136, v208, v136
	v_mul_f32_e32 v137, v208, v137
	v_mul_f32_e32 v138, v208, v138
	v_mul_f32_e32 v139, v208, v139
	v_cvt_pk_bf16_f32 v204, v136, v137
	v_cvt_pk_bf16_f32 v205, v138, v139
	v_mul_f32_e32 v140, v208, v140
	v_mul_f32_e32 v141, v208, v141
	v_mul_f32_e32 v142, v208, v142
	v_mul_f32_e32 v143, v208, v143
	v_cvt_pk_bf16_f32 v206, v140, v141
	v_cvt_pk_bf16_f32 v207, v142, v143
	s_mov_b64 exec, s[42:43]
	global_store_dwordx2 v190, v[200:201], s[34:35] offset:512 sc1
	global_store_dwordx2 v190, v[202:203], s[34:35] offset:544 sc1
	global_store_dwordx2 v190, v[204:205], s[34:35] offset:576 sc1
	global_store_dwordx2 v190, v[206:207], s[34:35] offset:608 sc1
	s_mov_b64 exec, -1
	s_mov_b64 s[20:21], s[28:29]
	s_mov_b64 s[22:23], s[30:31]
	s_add_u32 s24, s28, 0x80
	s_addc_u32 s25, s29, 0
	s_add_u32 s26, s30, 0x80
	s_addc_u32 s27, s31, 0
	s_mov_b64 s[34:35], s[36:37]
	s_mov_b32 s44, s45
	s_mov_b32 s2, s50
	s_cmp_lt_i32 s2, 0x8200
	s_cbranch_scc1 .Lattn_loop
